# EpiKV epilogue stores plain (no sc1 write-through); grid barrier wbl2 publishes them
# speedup vs baseline: 1.0170x; 1.0026x over previous
; #define wt16(p, v) wt16b(WSB, (p), (v))
; __device__ __forceinline__ u32x4 pack8(const float (&f)[8]) { u32x4 v; v.x = cvt_pk_bf16(f[0], f[1]); v.y = cvt_pk_bf16(f[2], f[3]); v.z = cvt_pk_bf16(f[4], f[5]); v.w = cvt_pk_bf16(f[6], f[7]); return v; }
;     __device__ __forceinline__ void operator()(const f32x4 (&acc)[2][2][4][2], const pg8::Unit& u, int wr, int wc, int fr, int fq) const {
;     ...
;                     for (int bj = 0; bj < 2; ++bj) {
;                         float o[8];
; #pragma unroll
;                         for (int e = 0; e < 8; ++e) o[e] = v[bj][e] * rk * khn[32 * bj + 8 * fq + e];
;                         wt16(kb + 32 * bj + 8 * fq, pack8(o));
;                     }
;                     float o[8];
; #pragma unroll
;                     for (int e = 0; e < 8; ++e) {
;                         const float mine = pe[e] * rk * khn[64 + 8 * fq + e];
;                         const float other = __shfl_xor(mine, 32);
;                         const float2 c = cs[(size_t)row * 16 + ((8 * fq + e) & 15)];
;                         o[e] = (fq < 2) ? (mine * c.x - other * c.y) : (other * c.y + mine * c.x);
;                     }
;                     wt16(kb + 64 + 8 * fq, pack8(o));
;                 } else {
;                     const int head = 4 * (pn - 2) + wc;
;                     bf16_t* vb = Vt + ((size_t)(b * 8 + head) * SEQ + s) * 64;
; #pragma unroll
;                     for (int bj = 0; bj < 2; ++bj) wt16(vb + 32 * bj + 8 * fq, pack8(v[bj]));
.LBB0_121:
	v_cvt_pk_bf16_f32 v8, v10, v11
	v_cvt_pk_bf16_f32 v9, v6, v7
	v_cvt_pk_bf16_f32 v10, v2, v3
	v_cvt_pk_bf16_f32 v11, v4, v5
	v_subrev_u32_e32 v0, s66, v22
	s_mov_b32 s58, s62
	s_mov_b32 s59, s63
	s_and_b64 vcc, exec, s[42:43]
	s_mov_b32 s46, s20
	s_mov_b32 s50, s10
	s_mov_b64 s[26:27], s[24:25]
	s_mov_b64 s[48:49], s[22:23]
	buffer_store_dwordx4 v[8:11], v0, s[56:59], 0 offen
	s_cbranch_vccnz .LBB0_165

; #define wt16(p, v) wt16b(WSB, (p), (v))
; __device__ __forceinline__ u32x4 pack8(const float (&f)[8]) { u32x4 v; v.x = cvt_pk_bf16(f[0], f[1]); v.y = cvt_pk_bf16(f[2], f[3]); v.z = cvt_pk_bf16(f[4], f[5]); v.w = cvt_pk_bf16(f[6], f[7]); return v; }
; __device__ __forceinline__ float sum4q(const f32x4 a) { return (a[0] + a[1]) + (a[2] + a[3]); }
;     __device__ __forceinline__ void operator()(const f32x4 (&acc)[2][2][4][2], const pg8::Unit& u, int wr, int wc, int fr, int fq) const {
;     ...
;             for (int m = 0; m < 4; ++m) { const int rw = row0 + ai * 128 + m * 16; rq[ai][m] = *(const f32x4*)(kvss + (size_t)rw * 4); }
; #pragma unroll
;         for (int ai = 0; ai < 2; ++ai)
; #pragma unroll
;             for (int m = 0; m < 4; ++m) {
;                 const int row = row0 + ai * 128 + m * 16; const float rkv = rsqrtf(sum4q(rq[ai][m]) * (1.f / 128.f) + EPS);
;                 const int b = row >> 11, s = row & (SEQ - 1);
;                 float v[2][8];
; #pragma unroll
;                 for (int bj = 0; bj < 2; ++bj)
; #pragma unroll
;                     for (int n = 0; n < 2; ++n)
; #pragma unroll
;                         for (int i = 0; i < 4; ++i) v[bj][4 * n + i] = acc[ai][bj][m][n][i] * rkv;
;                 if (pn < 2) {
;                     const int head = 4 * pn + wc;
;                     float ssn = 0.f;
; #pragma unroll
;                     for (int bj = 0; bj < 2; ++bj)
; #pragma unroll
;                         for (int e = 0; e < 8; ++e) ssn += v[bj][e] * v[bj][e];
;                     float pe[8]; unpack8(*(const u32x4*)(U + (size_t)row * NU + UPE + 8 * fq), pe);
; #pragma unroll
;                     for (int e = 0; e < 8; ++e) ssn += pe[e] * pe[e];
;                     ssn += __shfl_xor(ssn, 16); ssn += __shfl_xor(ssn, 32);
;                     const float rk = rsqrtf(ssn * (1.f / 96.f) + EPS);
;                     bf16_t* kb = Kf + ((size_t)(b * 8 + head) * SEQ + s) * 96;
;     ...
;                 } else {
;                     const int head = 4 * (pn - 2) + wc;
;                     bf16_t* vb = Vt + ((size_t)(b * 8 + head) * SEQ + s) * 64;
; #pragma unroll
;                     for (int bj = 0; bj < 2; ++bj) wt16(vb + 32 * bj + 8 * fq, pack8(v[bj]));
.LBB0_133:
	s_lshl_b32 s2, s50, 8
	s_add_i32 s28, s2, s34
	v_or_b32_e32 v198, s28, v167
	v_ashrrev_i32_e32 v199, 31, v198
	v_lshl_add_u64 v[50:51], v[198:199], 4, s[78:79]
	global_load_dwordx4 v[194:197], v[50:51], off
	v_or_b32_e32 v192, 16, v198
	v_ashrrev_i32_e32 v193, 31, v192
	v_or_b32_e32 v190, 32, v198
	v_lshl_add_u64 v[50:51], v[192:193], 4, s[78:79]
	v_ashrrev_i32_e32 v191, 31, v190
	v_or_b32_e32 v188, 48, v198
	global_load_dwordx4 v[154:157], v[50:51], off
	v_lshl_add_u64 v[50:51], v[190:191], 4, s[78:79]
	v_ashrrev_i32_e32 v189, 31, v188
	v_add_u32_e32 v186, 0x80, v198
	global_load_dwordx4 v[142:145], v[50:51], off
	v_lshl_add_u64 v[50:51], v[188:189], 4, s[78:79]
	v_ashrrev_i32_e32 v187, 31, v186
	v_add_u32_e32 v184, 0x90, v198
	global_load_dwordx4 v[130:133], v[50:51], off
	v_lshl_add_u64 v[50:51], v[186:187], 4, s[78:79]
	v_ashrrev_i32_e32 v185, 31, v184
	v_add_u32_e32 v182, 0xa0, v198
	global_load_dwordx4 v[110:113], v[50:51], off
	v_lshl_add_u64 v[50:51], v[184:185], 4, s[78:79]
	v_ashrrev_i32_e32 v183, 31, v182
	v_add_u32_e32 v180, 0xb0, v198
	global_load_dwordx4 v[90:93], v[50:51], off
	v_lshl_add_u64 v[50:51], v[182:183], 4, s[78:79]
	v_ashrrev_i32_e32 v181, 31, v180
	global_load_dwordx4 v[70:73], v[50:51], off
	v_lshl_add_u64 v[50:51], v[180:181], 4, s[78:79]
	global_load_dwordx4 v[50:53], v[50:51], off
	s_cmp_gt_i32 s46, 1
	s_cselect_b64 s[50:51], -1, 0
	s_lshl_b32 s2, s46, 2
	s_ashr_i32 s3, s28, 8
	s_add_i32 s21, s2, s12
	s_and_b32 s3, s3, -8
	s_add_i32 s26, s3, s21
	s_ashr_i32 s27, s26, 31
	s_lshl_b64 s[46:47], s[26:27], 18
	s_mov_b64 s[26:27], -1
	s_waitcnt vmcnt(0)
	v_mov_b32_e32 v200, v195
	v_mov_b32_e32 v201, v196
	v_mov_b32_e32 v195, v197
	v_pk_add_f32 v[194:195], v[200:201], v[194:195]
	s_nop 0
	v_add_f32_e32 v0, v194, v195
	v_fmamk_f32 v0, v0, 0x3c000000, v245
	v_cmp_gt_f32_e32 vcc, s83, v0
	v_mul_f32_e32 v194, 0x4b800000, v0
	s_nop 0
	v_cndmask_b32_e32 v0, v0, v194, vcc
	v_rsq_f32_e32 v0, v0
	s_nop 0
	v_mul_f32_e32 v194, 0x45800000, v0
	v_cndmask_b32_e32 v200, v0, v194, vcc
	v_mov_b32_e32 v0, 0x7cf
	v_pk_mul_f32 v[146:147], v[146:147], v[200:201] op_sel_hi:[1,0]
	v_pk_mul_f32 v[148:149], v[148:149], v[200:201] op_sel_hi:[1,0]
	v_pk_mul_f32 v[150:151], v[150:151], v[200:201] op_sel_hi:[1,0]
	v_pk_mul_f32 v[152:153], v[152:153], v[200:201] op_sel_hi:[1,0]
	v_bitop3_b32 v194, s28, v0, v167 bitop3:0xc8
	s_and_b64 vcc, exec, s[50:51]
	v_lshlrev_b32_e32 v0, 1, v166
	s_cbranch_vccz .LBB0_135
	v_readlane_b32 s26, v253, 34
	v_readlane_b32 s27, v253, 35
	s_add_u32 s26, s26, s46
	s_addc_u32 s27, s27, s47
	v_lshlrev_b32_e32 v196, 7, v194
	v_mov_b32_e32 v197, v1
	v_lshl_add_u64 v[202:203], s[26:27], 0, v[196:197]
	v_or3_b32 v195, v196, v0, s46
	v_lshl_add_u64 v[206:207], v[202:203], 0, v[0:1]
	v_cvt_pk_bf16_f32 v202, v146, v147
	v_cvt_pk_bf16_f32 v203, v148, v149
	v_cvt_pk_bf16_f32 v204, v150, v151
	v_cvt_pk_bf16_f32 v205, v152, v153
	v_add_u32_e32 v195, 0x17a00000, v195
	s_mov_b32 s58, s62
	s_mov_b32 s59, s63
	buffer_store_dwordx4 v[202:205], v195, s[56:59], 0 offen
	s_mov_b64 s[26:27], 0
	s_nop 0
	v_lshl_add_u64 v[204:205], v[206:207], 0, 64
.LBB0_135:
	s_or_b32 s28, s2, s92
	s_add_i32 s2, s3, s28
	s_ashr_i32 s3, s2, 31
	s_lshl_b64 s[48:49], s[2:3], 11
	v_pk_mul_f32 v[202:203], v[138:139], v[200:201] op_sel_hi:[1,0]
	v_pk_mul_f32 v[138:139], v[140:141], v[200:201] op_sel_hi:[1,0]
	v_pk_mul_f32 v[134:135], v[134:135], v[200:201] op_sel_hi:[1,0]
	s_andn2_b64 vcc, exec, s[26:27]
	v_pk_mul_f32 v[136:137], v[136:137], v[200:201] op_sel_hi:[1,0]
	s_cbranch_vccnz .LBB0_137
	v_mov_b64_e32 v[140:141], s[70:71]
	v_mad_i64_i32 v[140:141], s[2:3], v198, s85, v[140:141]
	v_lshl_add_u64 v[140:141], v[140:141], 0, v[0:1]
	v_add_co_u32_e32 v140, vcc, 0x1000, v140
	v_pk_mul_f32 v[196:197], v[148:149], v[148:149]
	s_nop 0
	v_addc_co_u32_e32 v141, vcc, 0, v141, vcc
	global_load_dwordx4 v[204:207], v[140:141], off offset:1792
	global_load_dwordx4 v[208:211], v[170:171], off
	global_load_dwordx4 v[212:215], v[170:171], off offset:16
	v_pk_mul_f32 v[140:141], v[146:147], v[146:147]
	v_pk_mul_f32 v[200:201], v[150:151], v[150:151]
	v_add_f32_e32 v140, v140, v141
	v_add_f32_e32 v140, v196, v140
	v_add_f32_e32 v140, v197, v140
	v_add_f32_e32 v140, v200, v140
	v_pk_mul_f32 v[216:217], v[152:153], v[152:153]
	v_add_f32_e32 v140, v201, v140
	v_add_f32_e32 v140, v216, v140
	v_pk_mul_f32 v[218:219], v[202:203], v[202:203]
	v_add_f32_e32 v140, v217, v140
	v_add_f32_e32 v140, v218, v140
	v_pk_mul_f32 v[220:221], v[138:139], v[138:139]
	v_add_f32_e32 v140, v219, v140
	v_add_f32_e32 v140, v220, v140
	v_pk_mul_f32 v[222:223], v[134:135], v[134:135]
	v_add_f32_e32 v140, v221, v140
	v_add_f32_e32 v140, v222, v140
	v_pk_mul_f32 v[224:225], v[136:137], v[136:137]
	v_add_f32_e32 v140, v223, v140
	v_add_f32_e32 v140, v224, v140
	v_and_b32_e32 v226, 64, v247
	v_add_f32_e32 v222, v225, v140
	v_xor_b32_e32 v195, 16, v247
	v_add_u32_e32 v226, 64, v226
	v_cmp_lt_i32_e32 vcc, v195, v226
	s_movk_i32 s26, 0xc0
	s_mov_b32 s58, s62
	v_cndmask_b32_e32 v141, v247, v195, vcc
	v_lshlrev_b32_e32 v195, 2, v141
	s_mov_b32 s59, s63
	v_readlane_b32 s2, v253, 32
	v_readlane_b32 s3, v253, 33
	s_waitcnt vmcnt(0)
; #define wt16(p, v) wt16b(WSB, (p), (v))
; __device__ __forceinline__ u32x4 pack8(const float (&f)[8]) { u32x4 v; v.x = cvt_pk_bf16(f[0], f[1]); v.y = cvt_pk_bf16(f[2], f[3]); v.z = cvt_pk_bf16(f[4], f[5]); v.w = cvt_pk_bf16(f[6], f[7]); return v; }
;     __device__ __forceinline__ void operator()(const f32x4 (&acc)[2][2][4][2], const pg8::Unit& u, int wr, int wc, int fr, int fq) const {
;     ...
;                     float pe[8]; unpack8(*(const u32x4*)(U + (size_t)row * NU + UPE + 8 * fq), pe);
; #pragma unroll
;                     for (int e = 0; e < 8; ++e) ssn += pe[e] * pe[e];
;                     ssn += __shfl_xor(ssn, 16); ssn += __shfl_xor(ssn, 32);
;                     const float rk = rsqrtf(ssn * (1.f / 96.f) + EPS);
;                     bf16_t* kb = Kf + ((size_t)(b * 8 + head) * SEQ + s) * 96;
; #pragma unroll
;                     for (int bj = 0; bj < 2; ++bj) {
;                         float o[8];
; #pragma unroll
;                         for (int e = 0; e < 8; ++e) o[e] = v[bj][e] * rk * khn[32 * bj + 8 * fq + e];
;                         wt16(kb + 32 * bj + 8 * fq, pack8(o));
;                     }
;                     float o[8];
; #pragma unroll
;                     for (int e = 0; e < 8; ++e) {
;                         const float mine = pe[e] * rk * khn[64 + 8 * fq + e];
;                         const float other = __shfl_xor(mine, 32);
;                         const float2 c = cs[(size_t)row * 16 + ((8 * fq + e) & 15)];
;                         o[e] = (fq < 2) ? (mine * c.x - other * c.y) : (other * c.y + mine * c.x);
;                     }
;                     wt16(kb + 64 + 8 * fq, pack8(o));
	v_lshlrev_b32_e32 v220, 16, v204
	v_and_b32_e32 v221, 0xffff0000, v204
	v_lshlrev_b32_e32 v218, 16, v205
	v_and_b32_e32 v219, 0xffff0000, v205
	v_pk_mul_f32 v[204:205], v[220:221], v[220:221]
	v_pk_mul_f32 v[200:201], v[218:219], v[218:219]
	v_add_f32_e32 v204, v222, v204
	v_add_f32_e32 v204, v205, v204
	v_and_b32_e32 v216, 0xffff0000, v206
	v_lshlrev_b32_e32 v217, 16, v206
	v_add_f32_e32 v200, v200, v204
	v_pk_mul_f32 v[140:141], v[216:217], v[216:217]
	v_add_f32_e32 v200, v201, v200
	v_and_b32_e32 v206, 0xffff0000, v207
	v_lshlrev_b32_e32 v207, 16, v207
	v_add_f32_e32 v141, v141, v200
	v_pk_mul_f32 v[196:197], v[206:207], v[206:207]
	v_add_f32_e32 v140, v140, v141
	v_add_f32_e32 v140, v197, v140
	v_add_f32_e32 v140, v196, v140
	ds_bpermute_b32 v141, v195, v140
	v_xor_b32_e32 v195, 32, v247
	v_cmp_lt_i32_e32 vcc, v195, v226
	v_or_b32_e32 v205, s48, v194
	v_mul_lo_u32 v194, v205, s26
	v_cndmask_b32_e32 v195, v247, v195, vcc
	v_lshlrev_b32_e32 v222, 2, v195
	s_waitcnt lgkmcnt(0)
	v_add_f32_e32 v140, v140, v141
	ds_bpermute_b32 v141, v222, v140
	v_add_u32_e32 v195, v194, v172
	v_add_u32_e32 v194, v174, v194
	s_waitcnt lgkmcnt(0)
	v_add_f32_e32 v140, v140, v141
	v_fmamk_f32 v140, v140, 0x3c2aaaab, v245
	v_mul_f32_e32 v141, 0x4b800000, v140
	v_cmp_gt_f32_e32 vcc, s83, v140
	s_nop 1
	v_cndmask_b32_e32 v140, v140, v141, vcc
	v_rsq_f32_e32 v140, v140
	s_nop 0
	v_mul_f32_e32 v141, 0x45800000, v140
	v_cndmask_b32_e32 v204, v140, v141, vcc
	v_pk_mul_f32 v[140:141], v[146:147], v[204:205] op_sel_hi:[1,0]
	v_pk_mul_f32 v[146:147], v[148:149], v[204:205] op_sel_hi:[1,0]
	v_pk_mul_f32 v[148:149], v[150:151], v[204:205] op_sel_hi:[1,0]
	v_pk_mul_f32 v[150:151], v[152:153], v[204:205] op_sel_hi:[1,0]
	v_pk_mul_f32 v[140:141], v[208:209], v[140:141]
	v_pk_mul_f32 v[152:153], v[210:211], v[146:147]
	v_pk_mul_f32 v[148:149], v[212:213], v[148:149]
	v_pk_mul_f32 v[150:151], v[214:215], v[150:151]
	v_cvt_pk_bf16_f32 v146, v140, v141
	v_cvt_pk_bf16_f32 v147, v152, v153
	v_cvt_pk_bf16_f32 v148, v148, v149
	v_cvt_pk_bf16_f32 v149, v150, v151
	buffer_store_dwordx4 v[146:149], v195, s[56:59], 0 offen
	global_load_dwordx4 v[146:149], v[170:171], off offset:128
	s_nop 0
	global_load_dwordx4 v[150:153], v[170:171], off offset:144
	v_lshlrev_b64 v[140:141], 7, v[198:199]
	v_lshl_add_u64 v[198:199], v[168:169], 0, v[140:141]
	v_pk_mul_f32 v[140:141], v[202:203], v[204:205] op_sel_hi:[1,0]
	v_pk_mul_f32 v[138:139], v[138:139], v[204:205] op_sel_hi:[1,0]
	v_pk_mul_f32 v[134:135], v[134:135], v[204:205] op_sel_hi:[1,0]
	v_pk_mul_f32 v[136:137], v[136:137], v[204:205] op_sel_hi:[1,0]
	v_mov_b64_e32 v[202:203], s[2:3]
	v_mad_u64_u32 v[202:203], s[2:3], v205, s26, v[202:203]
	v_mad_i32_i24 v203, s49, v243, v203
	v_lshl_add_u64 v[208:209], v[202:203], 0, v[0:1]
	v_pk_mul_f32 v[202:203], v[204:205], v[220:221] op_sel_hi:[0,1]
	v_pk_mul_f32 v[210:211], v[204:205], v[218:219] op_sel_hi:[0,1]
	v_pk_mul_f32 v[212:213], v[204:205], v[216:217] op_sel_hi:[0,1]
	v_pk_mul_f32 v[204:205], v[204:205], v[206:207] op_sel_hi:[0,1]
	s_waitcnt vmcnt(1)
	v_pk_mul_f32 v[140:141], v[146:147], v[140:141]
	v_pk_mul_f32 v[138:139], v[148:149], v[138:139]
	s_waitcnt vmcnt(0)
	v_pk_mul_f32 v[146:147], v[150:151], v[134:135]
	v_pk_mul_f32 v[148:149], v[152:153], v[136:137]
	v_cvt_pk_bf16_f32 v134, v140, v141
	v_cvt_pk_bf16_f32 v135, v138, v139
	v_cvt_pk_bf16_f32 v136, v146, v147
	v_cvt_pk_bf16_f32 v137, v148, v149
	buffer_store_dwordx4 v[134:137], v194, s[56:59], 0 offen
	global_load_dwordx4 v[134:137], v[170:171], off offset:256
	s_nop 0
	global_load_dwordx4 v[138:141], v[198:199], off
	global_load_dwordx4 v[146:149], v[198:199], off offset:16
	global_load_dwordx4 v[150:153], v[170:171], off offset:272
	global_load_dwordx4 v[194:197], v[198:199], off offset:32
	s_nop 0
	global_load_dwordx4 v[198:201], v[198:199], off offset:48
	s_waitcnt vmcnt(5)
	v_pk_mul_f32 v[134:135], v[202:203], v[134:135]
	s_waitcnt vmcnt(4)
	v_mov_b32_e32 v202, v138
	v_mov_b32_e32 v203, v140
	v_mov_b32_e32 v140, v139
	v_pk_mul_f32 v[136:137], v[210:211], v[136:137]
	s_waitcnt vmcnt(3)
	v_mov_b32_e32 v138, v146
	v_mov_b32_e32 v139, v148
	v_mov_b32_e32 v148, v147
	s_waitcnt vmcnt(2)
	v_pk_mul_f32 v[146:147], v[212:213], v[150:151] op_sel:[1,0] op_sel_hi:[0,1]
	v_pk_mul_f32 v[152:153], v[204:205], v[152:153] op_sel:[1,0] op_sel_hi:[0,1]
	ds_bpermute_b32 v204, v222, v134
	ds_bpermute_b32 v205, v222, v135
	ds_bpermute_b32 v206, v222, v136
	ds_bpermute_b32 v207, v222, v137
	ds_bpermute_b32 v210, v222, v146
	ds_bpermute_b32 v211, v222, v147
	ds_bpermute_b32 v212, v222, v152
	ds_bpermute_b32 v213, v222, v153
	s_waitcnt vmcnt(1)
	v_mov_b32_e32 v151, v196
	v_mov_b32_e32 v196, v195
	s_waitcnt vmcnt(0)
	v_mov_b32_e32 v195, v200
	v_mov_b32_e32 v200, v199
	v_mov_b32_e32 v150, v194
	v_mov_b32_e32 v194, v198
	s_waitcnt lgkmcnt(6)
	v_pk_mul_f32 v[140:141], v[140:141], v[204:205]
	s_waitcnt lgkmcnt(4)
	v_pk_mul_f32 v[148:149], v[148:149], v[206:207]
	s_waitcnt lgkmcnt(2)
	v_pk_mul_f32 v[196:197], v[196:197], v[210:211]
	s_waitcnt lgkmcnt(0)
	v_pk_mul_f32 v[198:199], v[200:201], v[212:213]
	v_cndmask_b32_e64 v141, v141, -v141, s[40:41]
	v_cndmask_b32_e64 v140, v140, -v140, s[40:41]
	v_cndmask_b32_e64 v149, v149, -v149, s[40:41]
	v_cndmask_b32_e64 v148, v148, -v148, s[40:41]
	v_cndmask_b32_e64 v197, v197, -v197, s[40:41]
	v_cndmask_b32_e64 v196, v196, -v196, s[40:41]
	v_cndmask_b32_e64 v199, v199, -v199, s[40:41]
	v_cndmask_b32_e64 v198, v198, -v198, s[40:41]
	v_pk_fma_f32 v[202:203], v[134:135], v[202:203], v[140:141]
	v_pk_fma_f32 v[138:139], v[136:137], v[138:139], v[148:149]
	v_pk_fma_f32 v[134:135], v[146:147], v[150:151], v[196:197]
	v_pk_fma_f32 v[136:137], v[152:153], v[194:195], v[198:199]
	v_lshl_add_u64 v[204:205], v[208:209], 0, s[80:81]
; #define wt16(p, v) wt16b(WSB, (p), (v))
;     __device__ __forceinline__ void operator()(const f32x4 (&acc)[2][2][4][2], const pg8::Unit& u, int wr, int wc, int fr, int fq) const {
;     ...
;         for (int ai = 0; ai < 2; ++ai)
; #pragma unroll
;             for (int m = 0; m < 4; ++m) {
;                 const int row = row0 + ai * 128 + m * 16; const float rkv = rsqrtf(sum4q(rq[ai][m]) * (1.f / 128.f) + EPS);
;                 const int b = row >> 11, s = row & (SEQ - 1);
;                 float v[2][8];
; #pragma unroll
;                 for (int bj = 0; bj < 2; ++bj)
; #pragma unroll
;                     for (int n = 0; n < 2; ++n)
; #pragma unroll
;                         for (int i = 0; i < 4; ++i) v[bj][4 * n + i] = acc[ai][bj][m][n][i] * rkv;
;                 if (pn < 2) {
;                     const int head = 4 * pn + wc;
;                     float ssn = 0.f;
; #pragma unroll
;                     for (int bj = 0; bj < 2; ++bj)
; #pragma unroll
;                         for (int e = 0; e < 8; ++e) ssn += v[bj][e] * v[bj][e];
;                     float pe[8]; unpack8(*(const u32x4*)(U + (size_t)row * NU + UPE + 8 * fq), pe);
; #pragma unroll
;                     for (int e = 0; e < 8; ++e) ssn += pe[e] * pe[e];
;                     ssn += __shfl_xor(ssn, 16); ssn += __shfl_xor(ssn, 32);
;                     const float rk = rsqrtf(ssn * (1.f / 96.f) + EPS);
;                     bf16_t* kb = Kf + ((size_t)(b * 8 + head) * SEQ + s) * 96;
; #pragma unroll
;                     for (int bj = 0; bj < 2; ++bj) {
;                         float o[8];
; #pragma unroll
;                         for (int e = 0; e < 8; ++e) o[e] = v[bj][e] * rk * khn[32 * bj + 8 * fq + e];
;                         wt16(kb + 32 * bj + 8 * fq, pack8(o));
;                     }
;                     float o[8];
; #pragma unroll
;                     for (int e = 0; e < 8; ++e) {
;                         const float mine = pe[e] * rk * khn[64 + 8 * fq + e];
;                         const float other = __shfl_xor(mine, 32);
;                         const float2 c = cs[(size_t)row * 16 + ((8 * fq + e) & 15)];
;                         o[e] = (fq < 2) ? (mine * c.x - other * c.y) : (other * c.y + mine * c.x);
;                     }
;                     wt16(kb + 64 + 8 * fq, pack8(o));
;                 } else {
;                     const int head = 4 * (pn - 2) + wc;
.LBB0_137:
	v_cvt_pk_bf16_f32 v148, v134, v135
	v_mov_b32_e32 v134, v155
	v_mov_b32_e32 v135, v156
	v_mov_b32_e32 v155, v157
	v_pk_add_f32 v[134:135], v[134:135], v[154:155]
	v_cvt_pk_bf16_f32 v146, v202, v203
	v_add_f32_e32 v134, v134, v135
	v_fmamk_f32 v134, v134, 0x3c000000, v245
	v_mul_f32_e32 v135, 0x4b800000, v134
	v_cmp_gt_f32_e32 vcc, s83, v134
	v_cvt_pk_bf16_f32 v147, v138, v139
	v_cvt_pk_bf16_f32 v149, v136, v137
	v_cndmask_b32_e32 v134, v134, v135, vcc
	v_rsq_f32_e32 v134, v134
	v_subrev_u32_e32 v136, s66, v204
	s_mov_b32 s58, s62
	s_mov_b32 s59, s63
	v_mul_f32_e32 v135, 0x45800000, v134
	buffer_store_dwordx4 v[146:149], v136, s[56:59], 0 offen
	v_cndmask_b32_e32 v136, v134, v135, vcc
	v_cndmask_b32_e64 v134, 0, 1, s[50:51]
	v_pk_mul_f32 v[126:127], v[126:127], v[136:137] op_sel_hi:[1,0]
	v_pk_mul_f32 v[128:129], v[128:129], v[136:137] op_sel_hi:[1,0]
	v_pk_mul_f32 v[122:123], v[122:123], v[136:137] op_sel_hi:[1,0]
	v_pk_mul_f32 v[124:125], v[124:125], v[136:137] op_sel_hi:[1,0]
	v_and_b32_e32 v137, 0x7df, v192
	v_cmp_ne_u32_e64 s[44:45], 1, v134
	s_andn2_b64 vcc, exec, s[50:51]
	s_mov_b64 s[2:3], -1
	s_cbranch_vccnz .LBB0_139
	v_readlane_b32 s2, v253, 34
	v_readlane_b32 s3, v253, 35
	s_add_u32 s2, s2, s46
	s_addc_u32 s3, s3, s47
	v_lshlrev_b32_e32 v134, 7, v137
	v_mov_b32_e32 v135, v1
	v_lshl_add_u64 v[138:139], s[2:3], 0, v[134:135]
	v_or3_b32 v134, v134, v0, s46
	v_lshl_add_u64 v[146:147], v[138:139], 0, v[0:1]
	v_cvt_pk_bf16_f32 v138, v126, v127
	v_cvt_pk_bf16_f32 v139, v128, v129
	v_cvt_pk_bf16_f32 v140, v122, v123
	v_cvt_pk_bf16_f32 v141, v124, v125
	v_add_u32_e32 v134, 0x17a00000, v134
	buffer_store_dwordx4 v[138:141], v134, s[56:59], 0 offen
	s_mov_b64 s[2:3], 0
	s_nop 0
	v_lshl_add_u64 v[138:139], v[146:147], 0, 64
.LBB0_139:
	v_pk_mul_f32 v[134:135], v[118:119], v[136:137] op_sel_hi:[1,0]
	v_pk_mul_f32 v[118:119], v[120:121], v[136:137] op_sel_hi:[1,0]
	v_pk_mul_f32 v[114:115], v[114:115], v[136:137] op_sel_hi:[1,0]
	s_andn2_b64 vcc, exec, s[2:3]
	v_pk_mul_f32 v[116:117], v[116:117], v[136:137] op_sel_hi:[1,0]
	s_cbranch_vccnz .LBB0_141
	v_mov_b64_e32 v[120:121], s[70:71]
	v_mad_i64_i32 v[120:121], s[2:3], v192, s85, v[120:121]
	v_lshl_add_u64 v[120:121], v[120:121], 0, v[0:1]
	v_add_co_u32_e32 v120, vcc, 0x1000, v120
	v_pk_mul_f32 v[154:155], v[128:129], v[128:129]
	s_nop 0
	v_addc_co_u32_e32 v121, vcc, 0, v121, vcc
	global_load_dwordx4 v[138:141], v[120:121], off offset:1792
	global_load_dwordx4 v[146:149], v[170:171], off
	global_load_dwordx4 v[150:153], v[170:171], off offset:16
	v_pk_mul_f32 v[120:121], v[126:127], v[126:127]
	v_pk_mul_f32 v[156:157], v[122:123], v[122:123]
	v_add_f32_e32 v120, v120, v121
	v_add_f32_e32 v120, v154, v120
	v_add_f32_e32 v120, v155, v120
	v_add_f32_e32 v120, v156, v120
	v_pk_mul_f32 v[194:195], v[124:125], v[124:125]
	v_add_f32_e32 v120, v157, v120
	v_add_f32_e32 v120, v194, v120
	v_pk_mul_f32 v[196:197], v[134:135], v[134:135]
	v_add_f32_e32 v120, v195, v120
	v_add_f32_e32 v120, v196, v120
	v_pk_mul_f32 v[198:199], v[118:119], v[118:119]
	v_add_f32_e32 v120, v197, v120
	v_add_f32_e32 v120, v198, v120
	v_pk_mul_f32 v[200:201], v[114:115], v[114:115]
	v_add_f32_e32 v120, v199, v120
	v_add_f32_e32 v120, v200, v120
	v_pk_mul_f32 v[202:203], v[116:117], v[116:117]
	v_add_f32_e32 v120, v201, v120
	v_add_f32_e32 v120, v202, v120
	v_and_b32_e32 v204, 64, v247
	v_add_f32_e32 v200, v203, v120
	v_xor_b32_e32 v136, 16, v247
	v_add_u32_e32 v204, 64, v204
	v_cmp_lt_i32_e32 vcc, v136, v204
	s_movk_i32 s26, 0xc0
	s_mov_b32 s58, s62
	v_cndmask_b32_e32 v121, v247, v136, vcc
	v_lshlrev_b32_e32 v136, 2, v121
	s_mov_b32 s59, s63
	v_readlane_b32 s2, v253, 32
	v_readlane_b32 s3, v253, 33
	s_waitcnt vmcnt(0)
	v_lshlrev_b32_e32 v196, 16, v138
	v_and_b32_e32 v197, 0xffff0000, v138
	v_pk_mul_f32 v[198:199], v[196:197], v[196:197]
	v_lshlrev_b32_e32 v194, 16, v139
	v_and_b32_e32 v195, 0xffff0000, v139
	v_add_f32_e32 v198, v200, v198
	v_and_b32_e32 v154, 0xffff0000, v140
	v_lshlrev_b32_e32 v155, 16, v140
	v_and_b32_e32 v156, 0xffff0000, v141
	v_lshlrev_b32_e32 v157, 16, v141
	v_pk_mul_f32 v[140:141], v[194:195], v[194:195]
	v_add_f32_e32 v198, v199, v198
	v_add_f32_e32 v140, v140, v198
	v_pk_mul_f32 v[120:121], v[154:155], v[154:155]
	v_add_f32_e32 v140, v141, v140
	v_add_f32_e32 v121, v121, v140
	v_pk_mul_f32 v[138:139], v[156:157], v[156:157]
	v_add_f32_e32 v120, v120, v121
	v_add_f32_e32 v120, v139, v120
	v_add_f32_e32 v120, v138, v120
	ds_bpermute_b32 v121, v136, v120
	v_xor_b32_e32 v136, 32, v247
	v_cmp_lt_i32_e32 vcc, v136, v204
	v_or_b32_e32 v200, s48, v137
	s_waitcnt lgkmcnt(0)
	v_add_f32_e32 v120, v120, v121
	v_cndmask_b32_e32 v136, v247, v136, vcc
	v_lshlrev_b32_e32 v199, 2, v136
	ds_bpermute_b32 v121, v199, v120
	v_mul_lo_u32 v136, v200, s26
	v_add_u32_e32 v137, v136, v172
	v_add_u32_e32 v136, v174, v136
	s_waitcnt lgkmcnt(0)
; #define wt16(p, v) wt16b(WSB, (p), (v))
;     __device__ __forceinline__ void operator()(const f32x4 (&acc)[2][2][4][2], const pg8::Unit& u, int wr, int wc, int fr, int fq) const {
;     ...
;         for (int ai = 0; ai < 2; ++ai)
; #pragma unroll
;             for (int m = 0; m < 4; ++m) {
;                 const int row = row0 + ai * 128 + m * 16; const float rkv = rsqrtf(sum4q(rq[ai][m]) * (1.f / 128.f) + EPS);
;                 const int b = row >> 11, s = row & (SEQ - 1);
;                 float v[2][8];
; #pragma unroll
;                 for (int bj = 0; bj < 2; ++bj)
; #pragma unroll
;                     for (int n = 0; n < 2; ++n)
; #pragma unroll
;                         for (int i = 0; i < 4; ++i) v[bj][4 * n + i] = acc[ai][bj][m][n][i] * rkv;
;                 if (pn < 2) {
;                     const int head = 4 * pn + wc;
;                     float ssn = 0.f;
; #pragma unroll
;                     for (int bj = 0; bj < 2; ++bj)
; #pragma unroll
;                         for (int e = 0; e < 8; ++e) ssn += v[bj][e] * v[bj][e];
;                     float pe[8]; unpack8(*(const u32x4*)(U + (size_t)row * NU + UPE + 8 * fq), pe);
; #pragma unroll
;                     for (int e = 0; e < 8; ++e) ssn += pe[e] * pe[e];
;                     ssn += __shfl_xor(ssn, 16); ssn += __shfl_xor(ssn, 32);
;                     const float rk = rsqrtf(ssn * (1.f / 96.f) + EPS);
;                     bf16_t* kb = Kf + ((size_t)(b * 8 + head) * SEQ + s) * 96;
; #pragma unroll
;                     for (int bj = 0; bj < 2; ++bj) {
;                         float o[8];
; #pragma unroll
;                         for (int e = 0; e < 8; ++e) o[e] = v[bj][e] * rk * khn[32 * bj + 8 * fq + e];
;                         wt16(kb + 32 * bj + 8 * fq, pack8(o));
;                     }
;                     float o[8];
; #pragma unroll
;                     for (int e = 0; e < 8; ++e) {
;                         const float mine = pe[e] * rk * khn[64 + 8 * fq + e];
;                         const float other = __shfl_xor(mine, 32);
;                         const float2 c = cs[(size_t)row * 16 + ((8 * fq + e) & 15)];
;                         o[e] = (fq < 2) ? (mine * c.x - other * c.y) : (other * c.y + mine * c.x);
;                     }
;                     wt16(kb + 64 + 8 * fq, pack8(o));
;                 } else {
;                     const int head = 4 * (pn - 2) + wc;
	v_add_f32_e32 v120, v120, v121
	v_fmamk_f32 v120, v120, 0x3c2aaaab, v245
	v_mul_f32_e32 v121, 0x4b800000, v120
	v_cmp_gt_f32_e32 vcc, s83, v120
	s_nop 1
	v_cndmask_b32_e32 v120, v120, v121, vcc
	v_rsq_f32_e32 v120, v120
	s_nop 0
	v_mul_f32_e32 v121, 0x45800000, v120
	v_cndmask_b32_e32 v198, v120, v121, vcc
	v_pk_mul_f32 v[120:121], v[126:127], v[198:199] op_sel_hi:[1,0]
	v_pk_mul_f32 v[126:127], v[128:129], v[198:199] op_sel_hi:[1,0]
	v_pk_mul_f32 v[122:123], v[122:123], v[198:199] op_sel_hi:[1,0]
	v_pk_mul_f32 v[124:125], v[124:125], v[198:199] op_sel_hi:[1,0]
	v_pk_mul_f32 v[120:121], v[146:147], v[120:121]
	v_pk_mul_f32 v[126:127], v[148:149], v[126:127]
	v_pk_mul_f32 v[122:123], v[150:151], v[122:123]
	v_pk_mul_f32 v[124:125], v[152:153], v[124:125]
	v_cvt_pk_bf16_f32 v120, v120, v121
	v_cvt_pk_bf16_f32 v121, v126, v127
	v_cvt_pk_bf16_f32 v122, v122, v123
	v_cvt_pk_bf16_f32 v123, v124, v125
	buffer_store_dwordx4 v[120:123], v137, s[56:59], 0 offen
	global_load_dwordx4 v[120:123], v[170:171], off offset:128
	s_nop 0
	global_load_dwordx4 v[124:127], v[170:171], off offset:144
	v_lshlrev_b64 v[128:129], 7, v[192:193]
	v_lshl_add_u64 v[138:139], v[168:169], 0, v[128:129]
	v_pk_mul_f32 v[128:129], v[134:135], v[198:199] op_sel_hi:[1,0]
	v_pk_mul_f32 v[118:119], v[118:119], v[198:199] op_sel_hi:[1,0]
	v_pk_mul_f32 v[114:115], v[114:115], v[198:199] op_sel_hi:[1,0]
	v_pk_mul_f32 v[116:117], v[116:117], v[198:199] op_sel_hi:[1,0]
	v_pk_mul_f32 v[148:149], v[198:199], v[196:197] op_sel_hi:[0,1]
	v_pk_mul_f32 v[150:151], v[198:199], v[194:195] op_sel_hi:[0,1]
	v_pk_mul_f32 v[152:153], v[198:199], v[154:155] op_sel_hi:[0,1]
	v_pk_mul_f32 v[154:155], v[198:199], v[156:157] op_sel_hi:[0,1]
	v_mov_b64_e32 v[146:147], s[2:3]
	v_mad_u64_u32 v[146:147], s[2:3], v200, s26, v[146:147]
	v_mad_i32_i24 v147, s49, v243, v147
	v_lshl_add_u64 v[146:147], v[146:147], 0, v[0:1]
	s_waitcnt vmcnt(1)
	v_pk_mul_f32 v[120:121], v[120:121], v[128:129]
	v_pk_mul_f32 v[118:119], v[122:123], v[118:119]
	s_waitcnt vmcnt(0)
	v_pk_mul_f32 v[122:123], v[124:125], v[114:115]
	v_pk_mul_f32 v[124:125], v[126:127], v[116:117]
	v_cvt_pk_bf16_f32 v114, v120, v121
	v_cvt_pk_bf16_f32 v115, v118, v119
	v_cvt_pk_bf16_f32 v116, v122, v123
	v_cvt_pk_bf16_f32 v117, v124, v125
	buffer_store_dwordx4 v[114:117], v136, s[56:59], 0 offen
	global_load_dwordx4 v[114:117], v[170:171], off offset:256
	s_nop 0
	global_load_dwordx4 v[118:121], v[138:139], off
	global_load_dwordx4 v[122:125], v[138:139], off offset:16
	global_load_dwordx4 v[126:129], v[170:171], off offset:272
	global_load_dwordx4 v[134:137], v[138:139], off offset:32
	s_nop 0
	global_load_dwordx4 v[138:141], v[138:139], off offset:48
	s_waitcnt vmcnt(5)
	v_pk_mul_f32 v[114:115], v[148:149], v[114:115]
	s_waitcnt vmcnt(4)
	v_mov_b32_e32 v148, v118
	v_mov_b32_e32 v149, v120
	v_mov_b32_e32 v120, v119
	v_pk_mul_f32 v[116:117], v[150:151], v[116:117]
	s_waitcnt vmcnt(3)
	v_mov_b32_e32 v118, v122
	v_mov_b32_e32 v119, v124
	v_mov_b32_e32 v124, v123
	s_waitcnt vmcnt(2)
	v_pk_mul_f32 v[122:123], v[152:153], v[126:127] op_sel:[1,0] op_sel_hi:[0,1]
	v_pk_mul_f32 v[128:129], v[154:155], v[128:129] op_sel:[1,0] op_sel_hi:[0,1]
	s_waitcnt vmcnt(1)
	v_mov_b32_e32 v126, v134
	v_mov_b32_e32 v127, v136
	v_mov_b32_e32 v136, v135
	ds_bpermute_b32 v134, v199, v114
	ds_bpermute_b32 v135, v199, v115
	ds_bpermute_b32 v152, v199, v116
	ds_bpermute_b32 v153, v199, v117
	ds_bpermute_b32 v154, v199, v122
	ds_bpermute_b32 v155, v199, v123
	ds_bpermute_b32 v156, v199, v128
	ds_bpermute_b32 v157, v199, v129
	s_waitcnt vmcnt(0)
	v_mov_b32_e32 v151, v140
	v_mov_b32_e32 v140, v139
	s_waitcnt lgkmcnt(6)
	v_pk_mul_f32 v[120:121], v[120:121], v[134:135]
	s_waitcnt lgkmcnt(4)
	v_pk_mul_f32 v[124:125], v[124:125], v[152:153]
	s_waitcnt lgkmcnt(2)
	v_pk_mul_f32 v[134:135], v[136:137], v[154:155]
	s_waitcnt lgkmcnt(0)
	v_pk_mul_f32 v[136:137], v[140:141], v[156:157]
	v_mov_b32_e32 v150, v138
	v_cndmask_b32_e64 v121, v121, -v121, s[40:41]
	v_cndmask_b32_e64 v120, v120, -v120, s[40:41]
	v_cndmask_b32_e64 v125, v125, -v125, s[40:41]
	v_cndmask_b32_e64 v124, v124, -v124, s[40:41]
	v_cndmask_b32_e64 v139, v135, -v135, s[40:41]
	v_cndmask_b32_e64 v138, v134, -v134, s[40:41]
	v_cndmask_b32_e64 v137, v137, -v137, s[40:41]
	v_cndmask_b32_e64 v136, v136, -v136, s[40:41]
	v_pk_fma_f32 v[134:135], v[114:115], v[148:149], v[120:121]
	v_pk_fma_f32 v[118:119], v[116:117], v[118:119], v[124:125]
	v_pk_fma_f32 v[114:115], v[122:123], v[126:127], v[138:139]
	v_pk_fma_f32 v[116:117], v[128:129], v[150:151], v[136:137]
	v_lshl_add_u64 v[138:139], v[146:147], 0, s[80:81]
.LBB0_141:
	v_cvt_pk_bf16_f32 v122, v114, v115
	v_mov_b32_e32 v114, v143
	v_mov_b32_e32 v115, v144
	v_mov_b32_e32 v143, v145
	v_pk_add_f32 v[114:115], v[114:115], v[142:143]
	v_cvt_pk_bf16_f32 v120, v134, v135
	v_add_f32_e32 v114, v114, v115
	v_fmamk_f32 v114, v114, 0x3c000000, v245
	v_mul_f32_e32 v115, 0x4b800000, v114
	v_cmp_gt_f32_e32 vcc, s83, v114
	v_cvt_pk_bf16_f32 v121, v118, v119
	v_cvt_pk_bf16_f32 v123, v116, v117
	v_cndmask_b32_e32 v114, v114, v115, vcc
	v_rsq_f32_e32 v114, v114
	v_subrev_u32_e32 v116, s66, v138
	s_mov_b32 s58, s62
	s_mov_b32 s59, s63
	v_mul_f32_e32 v115, 0x45800000, v114
	buffer_store_dwordx4 v[120:123], v116, s[56:59], 0 offen
	v_cndmask_b32_e32 v116, v114, v115, vcc
	v_pk_mul_f32 v[106:107], v[106:107], v[116:117] op_sel_hi:[1,0]
	v_pk_mul_f32 v[108:109], v[108:109], v[116:117] op_sel_hi:[1,0]
	v_pk_mul_f32 v[102:103], v[102:103], v[116:117] op_sel_hi:[1,0]
	v_pk_mul_f32 v[104:105], v[104:105], v[116:117] op_sel_hi:[1,0]
	v_and_b32_e32 v117, 0x7ef, v190
	s_and_b64 vcc, exec, s[44:45]
	s_mov_b64 s[2:3], -1
	s_cbranch_vccnz .LBB0_143
	v_readlane_b32 s2, v253, 34
	v_readlane_b32 s3, v253, 35
	s_add_u32 s2, s2, s46
	s_addc_u32 s3, s3, s47
	v_lshlrev_b32_e32 v114, 7, v117
	v_mov_b32_e32 v115, v1
	v_lshl_add_u64 v[118:119], s[2:3], 0, v[114:115]
	v_or3_b32 v114, v114, v0, s46
	v_lshl_add_u64 v[122:123], v[118:119], 0, v[0:1]
	v_cvt_pk_bf16_f32 v118, v106, v107
	v_cvt_pk_bf16_f32 v119, v108, v109
	v_cvt_pk_bf16_f32 v120, v102, v103
	v_cvt_pk_bf16_f32 v121, v104, v105
	v_add_u32_e32 v114, 0x17a00000, v114
	buffer_store_dwordx4 v[118:121], v114, s[56:59], 0 offen
	s_mov_b64 s[2:3], 0
	s_nop 0
	v_lshl_add_u64 v[118:119], v[122:123], 0, 64
; #define wt16(p, v) wt16b(WSB, (p), (v))
; __device__ __forceinline__ u32x4 pack8(const float (&f)[8]) { u32x4 v; v.x = cvt_pk_bf16(f[0], f[1]); v.y = cvt_pk_bf16(f[2], f[3]); v.z = cvt_pk_bf16(f[4], f[5]); v.w = cvt_pk_bf16(f[6], f[7]); return v; }
;     __device__ __forceinline__ void operator()(const f32x4 (&acc)[2][2][4][2], const pg8::Unit& u, int wr, int wc, int fr, int fq) const {
;     ...
;                 if (pn < 2) {
;                     const int head = 4 * pn + wc;
;                     float ssn = 0.f;
; #pragma unroll
;                     for (int bj = 0; bj < 2; ++bj)
; #pragma unroll
;                         for (int e = 0; e < 8; ++e) ssn += v[bj][e] * v[bj][e];
;                     float pe[8]; unpack8(*(const u32x4*)(U + (size_t)row * NU + UPE + 8 * fq), pe);
; #pragma unroll
;                     for (int e = 0; e < 8; ++e) ssn += pe[e] * pe[e];
;                     ssn += __shfl_xor(ssn, 16); ssn += __shfl_xor(ssn, 32);
;                     const float rk = rsqrtf(ssn * (1.f / 96.f) + EPS);
;                     bf16_t* kb = Kf + ((size_t)(b * 8 + head) * SEQ + s) * 96;
; #pragma unroll
;                     for (int bj = 0; bj < 2; ++bj) {
;                         float o[8];
; #pragma unroll
;                         for (int e = 0; e < 8; ++e) o[e] = v[bj][e] * rk * khn[32 * bj + 8 * fq + e];
;                         wt16(kb + 32 * bj + 8 * fq, pack8(o));
.LBB0_143:
	v_pk_mul_f32 v[114:115], v[98:99], v[116:117] op_sel_hi:[1,0]
	v_pk_mul_f32 v[98:99], v[100:101], v[116:117] op_sel_hi:[1,0]
	v_pk_mul_f32 v[94:95], v[94:95], v[116:117] op_sel_hi:[1,0]
	s_andn2_b64 vcc, exec, s[2:3]
	v_pk_mul_f32 v[96:97], v[96:97], v[116:117] op_sel_hi:[1,0]
	s_cbranch_vccnz .LBB0_145
	v_mov_b64_e32 v[100:101], s[70:71]
	v_mad_i64_i32 v[100:101], s[2:3], v190, s85, v[100:101]
	v_lshl_add_u64 v[100:101], v[100:101], 0, v[0:1]
	v_add_co_u32_e32 v100, vcc, 0x1000, v100
	v_pk_mul_f32 v[134:135], v[108:109], v[108:109]
	s_nop 0
	v_addc_co_u32_e32 v101, vcc, 0, v101, vcc
	global_load_dwordx4 v[118:121], v[100:101], off offset:1792
	global_load_dwordx4 v[122:125], v[170:171], off
	global_load_dwordx4 v[126:129], v[170:171], off offset:16
	v_pk_mul_f32 v[100:101], v[106:107], v[106:107]
	v_pk_mul_f32 v[136:137], v[102:103], v[102:103]
	v_add_f32_e32 v100, v100, v101
	v_add_f32_e32 v100, v134, v100
	v_add_f32_e32 v100, v135, v100
	v_add_f32_e32 v100, v136, v100
	v_pk_mul_f32 v[138:139], v[104:105], v[104:105]
	v_add_f32_e32 v100, v137, v100
	v_add_f32_e32 v100, v138, v100
	v_pk_mul_f32 v[140:141], v[114:115], v[114:115]
	v_add_f32_e32 v100, v139, v100
	v_add_f32_e32 v100, v140, v100
	v_pk_mul_f32 v[142:143], v[98:99], v[98:99]
	v_add_f32_e32 v100, v141, v100
	v_add_f32_e32 v100, v142, v100
	v_pk_mul_f32 v[144:145], v[94:95], v[94:95]
	v_add_f32_e32 v100, v143, v100
	v_add_f32_e32 v100, v144, v100
	v_pk_mul_f32 v[146:147], v[96:97], v[96:97]
	v_add_f32_e32 v100, v145, v100
	v_add_f32_e32 v100, v146, v100
	v_and_b32_e32 v148, 64, v247
	v_add_f32_e32 v144, v147, v100
	v_xor_b32_e32 v116, 16, v247
	v_add_u32_e32 v148, 64, v148
	v_cmp_lt_i32_e32 vcc, v116, v148
	s_movk_i32 s26, 0xc0
	s_mov_b32 s58, s62
	v_cndmask_b32_e32 v101, v247, v116, vcc
	v_lshlrev_b32_e32 v116, 2, v101
	s_mov_b32 s59, s63
	v_readlane_b32 s2, v253, 32
	v_readlane_b32 s3, v253, 33
	s_waitcnt vmcnt(0)
	v_lshlrev_b32_e32 v140, 16, v118
	v_and_b32_e32 v141, 0xffff0000, v118
	v_pk_mul_f32 v[142:143], v[140:141], v[140:141]
	v_lshlrev_b32_e32 v138, 16, v119
	v_and_b32_e32 v139, 0xffff0000, v119
	v_add_f32_e32 v142, v144, v142
	v_and_b32_e32 v134, 0xffff0000, v120
	v_lshlrev_b32_e32 v135, 16, v120
	v_and_b32_e32 v136, 0xffff0000, v121
	v_lshlrev_b32_e32 v137, 16, v121
	v_pk_mul_f32 v[120:121], v[138:139], v[138:139]
	v_add_f32_e32 v142, v143, v142
	v_add_f32_e32 v120, v120, v142
	v_pk_mul_f32 v[100:101], v[134:135], v[134:135]
	v_add_f32_e32 v120, v121, v120
	v_add_f32_e32 v101, v101, v120
	v_pk_mul_f32 v[118:119], v[136:137], v[136:137]
	v_add_f32_e32 v100, v100, v101
	v_add_f32_e32 v100, v119, v100
	v_add_f32_e32 v100, v118, v100
	ds_bpermute_b32 v101, v116, v100
	v_xor_b32_e32 v116, 32, v247
	v_cmp_lt_i32_e32 vcc, v116, v148
	v_or_b32_e32 v144, s48, v117
	s_waitcnt lgkmcnt(0)
	v_add_f32_e32 v100, v100, v101
	v_cndmask_b32_e32 v116, v247, v116, vcc
	v_lshlrev_b32_e32 v143, 2, v116
	ds_bpermute_b32 v101, v143, v100
	v_mul_lo_u32 v116, v144, s26
	v_add_u32_e32 v117, v116, v172
	v_add_u32_e32 v116, v174, v116
	s_waitcnt lgkmcnt(0)
	v_add_f32_e32 v100, v100, v101
	v_fmamk_f32 v100, v100, 0x3c2aaaab, v245
	v_mul_f32_e32 v101, 0x4b800000, v100
	v_cmp_gt_f32_e32 vcc, s83, v100
	s_nop 1
	v_cndmask_b32_e32 v100, v100, v101, vcc
	v_rsq_f32_e32 v100, v100
	s_nop 0
	v_mul_f32_e32 v101, 0x45800000, v100
	v_cndmask_b32_e32 v142, v100, v101, vcc
	v_pk_mul_f32 v[100:101], v[106:107], v[142:143] op_sel_hi:[1,0]
	v_pk_mul_f32 v[106:107], v[108:109], v[142:143] op_sel_hi:[1,0]
	v_pk_mul_f32 v[102:103], v[102:103], v[142:143] op_sel_hi:[1,0]
	v_pk_mul_f32 v[104:105], v[104:105], v[142:143] op_sel_hi:[1,0]
	v_pk_mul_f32 v[100:101], v[122:123], v[100:101]
	v_pk_mul_f32 v[106:107], v[124:125], v[106:107]
	v_pk_mul_f32 v[102:103], v[126:127], v[102:103]
	v_pk_mul_f32 v[104:105], v[128:129], v[104:105]
	v_cvt_pk_bf16_f32 v100, v100, v101
	v_cvt_pk_bf16_f32 v101, v106, v107
	v_cvt_pk_bf16_f32 v102, v102, v103
	v_cvt_pk_bf16_f32 v103, v104, v105
	buffer_store_dwordx4 v[100:103], v117, s[56:59], 0 offen
	global_load_dwordx4 v[100:103], v[170:171], off offset:128
	s_nop 0
	global_load_dwordx4 v[104:107], v[170:171], off offset:144
	v_lshlrev_b64 v[108:109], 7, v[190:191]
	v_lshl_add_u64 v[118:119], v[168:169], 0, v[108:109]
	v_pk_mul_f32 v[108:109], v[114:115], v[142:143] op_sel_hi:[1,0]
	v_pk_mul_f32 v[98:99], v[98:99], v[142:143] op_sel_hi:[1,0]
	v_pk_mul_f32 v[94:95], v[94:95], v[142:143] op_sel_hi:[1,0]
	v_pk_mul_f32 v[96:97], v[96:97], v[142:143] op_sel_hi:[1,0]
	v_pk_mul_f32 v[124:125], v[142:143], v[140:141] op_sel_hi:[0,1]
	v_pk_mul_f32 v[126:127], v[142:143], v[138:139] op_sel_hi:[0,1]
	v_pk_mul_f32 v[128:129], v[142:143], v[134:135] op_sel_hi:[0,1]
	v_pk_mul_f32 v[134:135], v[142:143], v[136:137] op_sel_hi:[0,1]
	v_mov_b64_e32 v[122:123], s[2:3]
	v_mad_u64_u32 v[122:123], s[2:3], v144, s26, v[122:123]
	v_mad_i32_i24 v123, s49, v243, v123
	v_lshl_add_u64 v[122:123], v[122:123], 0, v[0:1]
	s_waitcnt vmcnt(1)
	v_pk_mul_f32 v[100:101], v[100:101], v[108:109]
	v_pk_mul_f32 v[98:99], v[102:103], v[98:99]
	s_waitcnt vmcnt(0)
	v_pk_mul_f32 v[102:103], v[104:105], v[94:95]
	v_pk_mul_f32 v[104:105], v[106:107], v[96:97]
	v_cvt_pk_bf16_f32 v94, v100, v101
	v_cvt_pk_bf16_f32 v95, v98, v99
	v_cvt_pk_bf16_f32 v96, v102, v103
	v_cvt_pk_bf16_f32 v97, v104, v105
	buffer_store_dwordx4 v[94:97], v116, s[56:59], 0 offen
	global_load_dwordx4 v[94:97], v[170:171], off offset:256
	s_nop 0
	global_load_dwordx4 v[98:101], v[118:119], off
	global_load_dwordx4 v[102:105], v[118:119], off offset:16
	global_load_dwordx4 v[106:109], v[170:171], off offset:272
	global_load_dwordx4 v[114:117], v[118:119], off offset:32
	s_nop 0
	global_load_dwordx4 v[118:121], v[118:119], off offset:48
	s_waitcnt vmcnt(5)
; #define wt16(p, v) wt16b(WSB, (p), (v))
;     __device__ __forceinline__ void operator()(const f32x4 (&acc)[2][2][4][2], const pg8::Unit& u, int wr, int wc, int fr, int fq) const {
;     ...
;                 const int row = row0 + ai * 128 + m * 16; const float rkv = rsqrtf(sum4q(rq[ai][m]) * (1.f / 128.f) + EPS);
;                 const int b = row >> 11, s = row & (SEQ - 1);
;                 float v[2][8];
; #pragma unroll
;                 for (int bj = 0; bj < 2; ++bj)
; #pragma unroll
;                     for (int n = 0; n < 2; ++n)
; #pragma unroll
;                         for (int i = 0; i < 4; ++i) v[bj][4 * n + i] = acc[ai][bj][m][n][i] * rkv;
;                 if (pn < 2) {
;                     const int head = 4 * pn + wc;
;                     float ssn = 0.f;
; #pragma unroll
;                     for (int bj = 0; bj < 2; ++bj)
; #pragma unroll
;                         for (int e = 0; e < 8; ++e) ssn += v[bj][e] * v[bj][e];
;                     float pe[8]; unpack8(*(const u32x4*)(U + (size_t)row * NU + UPE + 8 * fq), pe);
; #pragma unroll
;                     for (int e = 0; e < 8; ++e) ssn += pe[e] * pe[e];
;                     ssn += __shfl_xor(ssn, 16); ssn += __shfl_xor(ssn, 32);
;                     const float rk = rsqrtf(ssn * (1.f / 96.f) + EPS);
;                     bf16_t* kb = Kf + ((size_t)(b * 8 + head) * SEQ + s) * 96;
; #pragma unroll
;                     for (int bj = 0; bj < 2; ++bj) {
;                         float o[8];
; #pragma unroll
;                         for (int e = 0; e < 8; ++e) o[e] = v[bj][e] * rk * khn[32 * bj + 8 * fq + e];
;                         wt16(kb + 32 * bj + 8 * fq, pack8(o));
;                     }
;                     float o[8];
; #pragma unroll
;                     for (int e = 0; e < 8; ++e) {
;                         const float mine = pe[e] * rk * khn[64 + 8 * fq + e];
;                         const float other = __shfl_xor(mine, 32);
;                         const float2 c = cs[(size_t)row * 16 + ((8 * fq + e) & 15)];
;                         o[e] = (fq < 2) ? (mine * c.x - other * c.y) : (other * c.y + mine * c.x);
;                     }
;                     wt16(kb + 64 + 8 * fq, pack8(o));
;                 } else {
;                     const int head = 4 * (pn - 2) + wc;
;                     bf16_t* vb = Vt + ((size_t)(b * 8 + head) * SEQ + s) * 64;
; #pragma unroll
	v_pk_mul_f32 v[94:95], v[124:125], v[94:95]
	s_waitcnt vmcnt(4)
	v_mov_b32_e32 v124, v98
	v_mov_b32_e32 v125, v100
	v_mov_b32_e32 v100, v99
	v_pk_mul_f32 v[96:97], v[126:127], v[96:97]
	s_waitcnt vmcnt(3)
	v_mov_b32_e32 v98, v102
	v_mov_b32_e32 v99, v104
	v_mov_b32_e32 v104, v103
	s_waitcnt vmcnt(2)
	v_pk_mul_f32 v[102:103], v[128:129], v[106:107] op_sel:[1,0] op_sel_hi:[0,1]
	v_pk_mul_f32 v[108:109], v[134:135], v[108:109] op_sel:[1,0] op_sel_hi:[0,1]
	s_waitcnt vmcnt(1)
	v_mov_b32_e32 v106, v114
	v_mov_b32_e32 v107, v116
	v_mov_b32_e32 v116, v115
	ds_bpermute_b32 v114, v143, v94
	ds_bpermute_b32 v115, v143, v95
	ds_bpermute_b32 v128, v143, v96
	ds_bpermute_b32 v129, v143, v97
	ds_bpermute_b32 v134, v143, v102
	ds_bpermute_b32 v135, v143, v103
	ds_bpermute_b32 v136, v143, v108
	ds_bpermute_b32 v137, v143, v109
	s_waitcnt vmcnt(0)
	v_mov_b32_e32 v127, v120
	v_mov_b32_e32 v120, v119
	s_waitcnt lgkmcnt(6)
	v_pk_mul_f32 v[100:101], v[100:101], v[114:115]
	s_waitcnt lgkmcnt(4)
	v_pk_mul_f32 v[104:105], v[104:105], v[128:129]
	s_waitcnt lgkmcnt(2)
	v_pk_mul_f32 v[114:115], v[116:117], v[134:135]
	s_waitcnt lgkmcnt(0)
	v_pk_mul_f32 v[116:117], v[120:121], v[136:137]
	v_mov_b32_e32 v126, v118
	v_cndmask_b32_e64 v101, v101, -v101, s[40:41]
	v_cndmask_b32_e64 v100, v100, -v100, s[40:41]
	v_cndmask_b32_e64 v105, v105, -v105, s[40:41]
	v_cndmask_b32_e64 v104, v104, -v104, s[40:41]
	v_cndmask_b32_e64 v119, v115, -v115, s[40:41]
	v_cndmask_b32_e64 v118, v114, -v114, s[40:41]
	v_cndmask_b32_e64 v117, v117, -v117, s[40:41]
	v_cndmask_b32_e64 v116, v116, -v116, s[40:41]
	v_pk_fma_f32 v[114:115], v[94:95], v[124:125], v[100:101]
	v_pk_fma_f32 v[98:99], v[96:97], v[98:99], v[104:105]
	v_pk_fma_f32 v[94:95], v[102:103], v[106:107], v[118:119]
	v_pk_fma_f32 v[96:97], v[108:109], v[126:127], v[116:117]
	v_lshl_add_u64 v[118:119], v[122:123], 0, s[80:81]
.LBB0_145:
	v_cvt_pk_bf16_f32 v102, v94, v95
	v_mov_b32_e32 v94, v131
	v_mov_b32_e32 v95, v132
	v_mov_b32_e32 v131, v133
	v_pk_add_f32 v[94:95], v[94:95], v[130:131]
	v_cvt_pk_bf16_f32 v100, v114, v115
	v_add_f32_e32 v94, v94, v95
	v_fmamk_f32 v94, v94, 0x3c000000, v245
	v_mul_f32_e32 v95, 0x4b800000, v94
	v_cmp_gt_f32_e32 vcc, s83, v94
	v_cvt_pk_bf16_f32 v101, v98, v99
	v_cvt_pk_bf16_f32 v103, v96, v97
	v_cndmask_b32_e32 v94, v94, v95, vcc
	v_rsq_f32_e32 v94, v94
	v_subrev_u32_e32 v96, s66, v118
	s_mov_b32 s58, s62
	s_mov_b32 s59, s63
	v_mul_f32_e32 v95, 0x45800000, v94
	buffer_store_dwordx4 v[100:103], v96, s[56:59], 0 offen
	v_cndmask_b32_e32 v96, v94, v95, vcc
	v_pk_mul_f32 v[86:87], v[86:87], v[96:97] op_sel_hi:[1,0]
	v_pk_mul_f32 v[88:89], v[88:89], v[96:97] op_sel_hi:[1,0]
	v_pk_mul_f32 v[82:83], v[82:83], v[96:97] op_sel_hi:[1,0]
	v_pk_mul_f32 v[84:85], v[84:85], v[96:97] op_sel_hi:[1,0]
	v_and_b32_e32 v97, 0x7ff, v188
	s_and_b64 vcc, exec, s[44:45]
	s_mov_b64 s[2:3], -1
	s_cbranch_vccnz .LBB0_147
	v_readlane_b32 s2, v253, 34
	v_readlane_b32 s3, v253, 35
	s_add_u32 s2, s2, s46
	s_addc_u32 s3, s3, s47
	v_lshlrev_b32_e32 v94, 7, v97
	v_mov_b32_e32 v95, v1
	v_lshl_add_u64 v[98:99], s[2:3], 0, v[94:95]
	v_or3_b32 v94, v94, v0, s46
	v_lshl_add_u64 v[102:103], v[98:99], 0, v[0:1]
	v_cvt_pk_bf16_f32 v98, v86, v87
	v_cvt_pk_bf16_f32 v99, v88, v89
	v_cvt_pk_bf16_f32 v100, v82, v83
	v_cvt_pk_bf16_f32 v101, v84, v85
	v_add_u32_e32 v94, 0x17a00000, v94
	buffer_store_dwordx4 v[98:101], v94, s[56:59], 0 offen
	s_mov_b64 s[2:3], 0
	s_nop 0
	v_lshl_add_u64 v[98:99], v[102:103], 0, 64
.LBB0_147:
	v_pk_mul_f32 v[94:95], v[78:79], v[96:97] op_sel_hi:[1,0]
	v_pk_mul_f32 v[78:79], v[80:81], v[96:97] op_sel_hi:[1,0]
	v_pk_mul_f32 v[74:75], v[74:75], v[96:97] op_sel_hi:[1,0]
	s_andn2_b64 vcc, exec, s[2:3]
	v_pk_mul_f32 v[76:77], v[76:77], v[96:97] op_sel_hi:[1,0]
	s_cbranch_vccnz .LBB0_149
	v_mov_b64_e32 v[80:81], s[70:71]
	v_mad_i64_i32 v[80:81], s[2:3], v188, s85, v[80:81]
	v_lshl_add_u64 v[80:81], v[80:81], 0, v[0:1]
	v_add_co_u32_e32 v80, vcc, 0x1000, v80
	v_pk_mul_f32 v[114:115], v[88:89], v[88:89]
	s_nop 0
	v_addc_co_u32_e32 v81, vcc, 0, v81, vcc
	global_load_dwordx4 v[98:101], v[80:81], off offset:1792
	global_load_dwordx4 v[102:105], v[170:171], off
	global_load_dwordx4 v[106:109], v[170:171], off offset:16
	v_pk_mul_f32 v[80:81], v[86:87], v[86:87]
	v_pk_mul_f32 v[116:117], v[82:83], v[82:83]
	v_add_f32_e32 v80, v80, v81
	v_add_f32_e32 v80, v114, v80
	v_add_f32_e32 v80, v115, v80
	v_add_f32_e32 v80, v116, v80
	v_pk_mul_f32 v[118:119], v[84:85], v[84:85]
	v_add_f32_e32 v80, v117, v80
	v_add_f32_e32 v80, v118, v80
	v_pk_mul_f32 v[120:121], v[94:95], v[94:95]
	v_add_f32_e32 v80, v119, v80
	v_add_f32_e32 v80, v120, v80
	v_pk_mul_f32 v[122:123], v[78:79], v[78:79]
	v_add_f32_e32 v80, v121, v80
	v_add_f32_e32 v80, v122, v80
	v_pk_mul_f32 v[124:125], v[74:75], v[74:75]
	v_add_f32_e32 v80, v123, v80
	v_add_f32_e32 v80, v124, v80
	v_pk_mul_f32 v[126:127], v[76:77], v[76:77]
	v_add_f32_e32 v80, v125, v80
	v_add_f32_e32 v80, v126, v80
	v_and_b32_e32 v128, 64, v247
	v_add_f32_e32 v124, v127, v80
	v_xor_b32_e32 v96, 16, v247
	v_add_u32_e32 v128, 64, v128
	v_cmp_lt_i32_e32 vcc, v96, v128
	s_movk_i32 s26, 0xc0
	s_mov_b32 s58, s62
	v_cndmask_b32_e32 v81, v247, v96, vcc
	v_lshlrev_b32_e32 v96, 2, v81
	s_mov_b32 s59, s63
	v_readlane_b32 s2, v253, 32
	v_readlane_b32 s3, v253, 33
	s_waitcnt vmcnt(0)
; #define wt16(p, v) wt16b(WSB, (p), (v))
; __device__ __forceinline__ u32x4 pack8(const float (&f)[8]) { u32x4 v; v.x = cvt_pk_bf16(f[0], f[1]); v.y = cvt_pk_bf16(f[2], f[3]); v.z = cvt_pk_bf16(f[4], f[5]); v.w = cvt_pk_bf16(f[6], f[7]); return v; }
;     __device__ __forceinline__ void operator()(const f32x4 (&acc)[2][2][4][2], const pg8::Unit& u, int wr, int wc, int fr, int fq) const {
;     ...
;                         for (int e = 0; e < 8; ++e) ssn += v[bj][e] * v[bj][e];
;                     float pe[8]; unpack8(*(const u32x4*)(U + (size_t)row * NU + UPE + 8 * fq), pe);
; #pragma unroll
;                     for (int e = 0; e < 8; ++e) ssn += pe[e] * pe[e];
;                     ssn += __shfl_xor(ssn, 16); ssn += __shfl_xor(ssn, 32);
;                     const float rk = rsqrtf(ssn * (1.f / 96.f) + EPS);
;                     bf16_t* kb = Kf + ((size_t)(b * 8 + head) * SEQ + s) * 96;
; #pragma unroll
;                     for (int bj = 0; bj < 2; ++bj) {
;                         float o[8];
; #pragma unroll
;                         for (int e = 0; e < 8; ++e) o[e] = v[bj][e] * rk * khn[32 * bj + 8 * fq + e];
;                         wt16(kb + 32 * bj + 8 * fq, pack8(o));
;                     }
;                     float o[8];
; #pragma unroll
;                     for (int e = 0; e < 8; ++e) {
;                         const float mine = pe[e] * rk * khn[64 + 8 * fq + e];
;                         const float other = __shfl_xor(mine, 32);
;                         const float2 c = cs[(size_t)row * 16 + ((8 * fq + e) & 15)];
;                         o[e] = (fq < 2) ? (mine * c.x - other * c.y) : (other * c.y + mine * c.x);
;                     }
;                     wt16(kb + 64 + 8 * fq, pack8(o));
	v_lshlrev_b32_e32 v120, 16, v98
	v_and_b32_e32 v121, 0xffff0000, v98
	v_pk_mul_f32 v[122:123], v[120:121], v[120:121]
	v_lshlrev_b32_e32 v118, 16, v99
	v_and_b32_e32 v119, 0xffff0000, v99
	v_add_f32_e32 v122, v124, v122
	v_and_b32_e32 v114, 0xffff0000, v100
	v_lshlrev_b32_e32 v115, 16, v100
	v_and_b32_e32 v116, 0xffff0000, v101
	v_lshlrev_b32_e32 v117, 16, v101
	v_pk_mul_f32 v[100:101], v[118:119], v[118:119]
	v_add_f32_e32 v122, v123, v122
	v_add_f32_e32 v100, v100, v122
	v_pk_mul_f32 v[80:81], v[114:115], v[114:115]
	v_add_f32_e32 v100, v101, v100
	v_add_f32_e32 v81, v81, v100
	v_pk_mul_f32 v[98:99], v[116:117], v[116:117]
	v_add_f32_e32 v80, v80, v81
	v_add_f32_e32 v80, v99, v80
	v_add_f32_e32 v80, v98, v80
	ds_bpermute_b32 v81, v96, v80
	v_xor_b32_e32 v96, 32, v247
	v_cmp_lt_i32_e32 vcc, v96, v128
	v_or_b32_e32 v124, s48, v97
	s_waitcnt lgkmcnt(0)
	v_add_f32_e32 v80, v80, v81
	v_cndmask_b32_e32 v96, v247, v96, vcc
	v_lshlrev_b32_e32 v123, 2, v96
	ds_bpermute_b32 v81, v123, v80
	v_mul_lo_u32 v96, v124, s26
	v_add_u32_e32 v97, v96, v172
	v_add_u32_e32 v96, v174, v96
	s_waitcnt lgkmcnt(0)
	v_add_f32_e32 v80, v80, v81
	v_fmamk_f32 v80, v80, 0x3c2aaaab, v245
	v_mul_f32_e32 v81, 0x4b800000, v80
	v_cmp_gt_f32_e32 vcc, s83, v80
	s_nop 1
	v_cndmask_b32_e32 v80, v80, v81, vcc
	v_rsq_f32_e32 v80, v80
	s_nop 0
	v_mul_f32_e32 v81, 0x45800000, v80
	v_cndmask_b32_e32 v122, v80, v81, vcc
	v_pk_mul_f32 v[80:81], v[86:87], v[122:123] op_sel_hi:[1,0]
	v_pk_mul_f32 v[86:87], v[88:89], v[122:123] op_sel_hi:[1,0]
	v_pk_mul_f32 v[82:83], v[82:83], v[122:123] op_sel_hi:[1,0]
	v_pk_mul_f32 v[84:85], v[84:85], v[122:123] op_sel_hi:[1,0]
	v_pk_mul_f32 v[80:81], v[102:103], v[80:81]
	v_pk_mul_f32 v[86:87], v[104:105], v[86:87]
	v_pk_mul_f32 v[82:83], v[106:107], v[82:83]
	v_pk_mul_f32 v[84:85], v[108:109], v[84:85]
	v_cvt_pk_bf16_f32 v80, v80, v81
	v_cvt_pk_bf16_f32 v81, v86, v87
	v_cvt_pk_bf16_f32 v82, v82, v83
	v_cvt_pk_bf16_f32 v83, v84, v85
	buffer_store_dwordx4 v[80:83], v97, s[56:59], 0 offen
	global_load_dwordx4 v[80:83], v[170:171], off offset:128
	s_nop 0
	global_load_dwordx4 v[84:87], v[170:171], off offset:144
	v_lshlrev_b64 v[88:89], 7, v[188:189]
	v_lshl_add_u64 v[98:99], v[168:169], 0, v[88:89]
	v_pk_mul_f32 v[88:89], v[94:95], v[122:123] op_sel_hi:[1,0]
	v_pk_mul_f32 v[78:79], v[78:79], v[122:123] op_sel_hi:[1,0]
	v_pk_mul_f32 v[74:75], v[74:75], v[122:123] op_sel_hi:[1,0]
	v_pk_mul_f32 v[76:77], v[76:77], v[122:123] op_sel_hi:[1,0]
	v_pk_mul_f32 v[104:105], v[122:123], v[120:121] op_sel_hi:[0,1]
	v_pk_mul_f32 v[106:107], v[122:123], v[118:119] op_sel_hi:[0,1]
	v_pk_mul_f32 v[108:109], v[122:123], v[114:115] op_sel_hi:[0,1]
	v_pk_mul_f32 v[114:115], v[122:123], v[116:117] op_sel_hi:[0,1]
	v_mov_b64_e32 v[102:103], s[2:3]
	v_mad_u64_u32 v[102:103], s[2:3], v124, s26, v[102:103]
	v_mad_i32_i24 v103, s49, v243, v103
	v_lshl_add_u64 v[102:103], v[102:103], 0, v[0:1]
	s_waitcnt vmcnt(1)
	v_pk_mul_f32 v[80:81], v[80:81], v[88:89]
	v_pk_mul_f32 v[78:79], v[82:83], v[78:79]
	s_waitcnt vmcnt(0)
	v_pk_mul_f32 v[82:83], v[84:85], v[74:75]
	v_pk_mul_f32 v[84:85], v[86:87], v[76:77]
	v_cvt_pk_bf16_f32 v74, v80, v81
	v_cvt_pk_bf16_f32 v75, v78, v79
	v_cvt_pk_bf16_f32 v76, v82, v83
	v_cvt_pk_bf16_f32 v77, v84, v85
	buffer_store_dwordx4 v[74:77], v96, s[56:59], 0 offen
	global_load_dwordx4 v[74:77], v[170:171], off offset:256
	s_nop 0
	global_load_dwordx4 v[78:81], v[98:99], off
	global_load_dwordx4 v[82:85], v[98:99], off offset:16
	global_load_dwordx4 v[86:89], v[170:171], off offset:272
	global_load_dwordx4 v[94:97], v[98:99], off offset:32
	s_nop 0
	global_load_dwordx4 v[98:101], v[98:99], off offset:48
	s_waitcnt vmcnt(5)
	v_pk_mul_f32 v[74:75], v[104:105], v[74:75]
	s_waitcnt vmcnt(4)
	v_mov_b32_e32 v104, v78
	v_mov_b32_e32 v105, v80
	v_mov_b32_e32 v80, v79
	v_pk_mul_f32 v[76:77], v[106:107], v[76:77]
	s_waitcnt vmcnt(3)
	v_mov_b32_e32 v78, v82
	v_mov_b32_e32 v79, v84
	v_mov_b32_e32 v84, v83
	s_waitcnt vmcnt(2)
	v_pk_mul_f32 v[82:83], v[108:109], v[86:87] op_sel:[1,0] op_sel_hi:[0,1]
	v_pk_mul_f32 v[88:89], v[114:115], v[88:89] op_sel:[1,0] op_sel_hi:[0,1]
	s_waitcnt vmcnt(1)
	v_mov_b32_e32 v86, v94
	v_mov_b32_e32 v87, v96
	v_mov_b32_e32 v96, v95
	ds_bpermute_b32 v94, v123, v74
	ds_bpermute_b32 v95, v123, v75
	ds_bpermute_b32 v108, v123, v76
	ds_bpermute_b32 v109, v123, v77
	ds_bpermute_b32 v114, v123, v82
	ds_bpermute_b32 v115, v123, v83
	ds_bpermute_b32 v116, v123, v88
	ds_bpermute_b32 v117, v123, v89
	s_waitcnt vmcnt(0)
	v_mov_b32_e32 v107, v100
	v_mov_b32_e32 v100, v99
	s_waitcnt lgkmcnt(6)
	v_pk_mul_f32 v[80:81], v[80:81], v[94:95]
	s_waitcnt lgkmcnt(4)
	v_pk_mul_f32 v[84:85], v[84:85], v[108:109]
	s_waitcnt lgkmcnt(2)
	v_pk_mul_f32 v[94:95], v[96:97], v[114:115]
	s_waitcnt lgkmcnt(0)
	v_pk_mul_f32 v[96:97], v[100:101], v[116:117]
	v_mov_b32_e32 v106, v98
	v_cndmask_b32_e64 v81, v81, -v81, s[40:41]
	v_cndmask_b32_e64 v80, v80, -v80, s[40:41]
	v_cndmask_b32_e64 v85, v85, -v85, s[40:41]
	v_cndmask_b32_e64 v84, v84, -v84, s[40:41]
	v_cndmask_b32_e64 v99, v95, -v95, s[40:41]
	v_cndmask_b32_e64 v98, v94, -v94, s[40:41]
	v_cndmask_b32_e64 v97, v97, -v97, s[40:41]
	v_cndmask_b32_e64 v96, v96, -v96, s[40:41]
	v_pk_fma_f32 v[94:95], v[74:75], v[104:105], v[80:81]
	v_pk_fma_f32 v[78:79], v[76:77], v[78:79], v[84:85]
	v_pk_fma_f32 v[74:75], v[82:83], v[86:87], v[98:99]
	v_pk_fma_f32 v[76:77], v[88:89], v[106:107], v[96:97]
	v_lshl_add_u64 v[98:99], v[102:103], 0, s[80:81]
; #define wt16(p, v) wt16b(WSB, (p), (v))
;     __device__ __forceinline__ void operator()(const f32x4 (&acc)[2][2][4][2], const pg8::Unit& u, int wr, int wc, int fr, int fq) const {
;     ...
;                 const int row = row0 + ai * 128 + m * 16; const float rkv = rsqrtf(sum4q(rq[ai][m]) * (1.f / 128.f) + EPS);
;                 const int b = row >> 11, s = row & (SEQ - 1);
;                 float v[2][8];
; #pragma unroll
;                 for (int bj = 0; bj < 2; ++bj)
; #pragma unroll
;                     for (int n = 0; n < 2; ++n)
; #pragma unroll
;                         for (int i = 0; i < 4; ++i) v[bj][4 * n + i] = acc[ai][bj][m][n][i] * rkv;
;                 if (pn < 2) {
;                     const int head = 4 * pn + wc;
;                     float ssn = 0.f;
; #pragma unroll
;                     for (int bj = 0; bj < 2; ++bj)
; #pragma unroll
;                         for (int e = 0; e < 8; ++e) ssn += v[bj][e] * v[bj][e];
;                     float pe[8]; unpack8(*(const u32x4*)(U + (size_t)row * NU + UPE + 8 * fq), pe);
; #pragma unroll
;                     for (int e = 0; e < 8; ++e) ssn += pe[e] * pe[e];
;                     ssn += __shfl_xor(ssn, 16); ssn += __shfl_xor(ssn, 32);
;                     const float rk = rsqrtf(ssn * (1.f / 96.f) + EPS);
;                     bf16_t* kb = Kf + ((size_t)(b * 8 + head) * SEQ + s) * 96;
; #pragma unroll
;                     for (int bj = 0; bj < 2; ++bj) {
;                         float o[8];
; #pragma unroll
;                         for (int e = 0; e < 8; ++e) o[e] = v[bj][e] * rk * khn[32 * bj + 8 * fq + e];
;                         wt16(kb + 32 * bj + 8 * fq, pack8(o));
;                     }
;                     float o[8];
; #pragma unroll
;                     for (int e = 0; e < 8; ++e) {
;                         const float mine = pe[e] * rk * khn[64 + 8 * fq + e];
;                         const float other = __shfl_xor(mine, 32);
;                         const float2 c = cs[(size_t)row * 16 + ((8 * fq + e) & 15)];
;                         o[e] = (fq < 2) ? (mine * c.x - other * c.y) : (other * c.y + mine * c.x);
;                     }
;                     wt16(kb + 64 + 8 * fq, pack8(o));
;                 } else {
;                     const int head = 4 * (pn - 2) + wc;
;                     bf16_t* vb = Vt + ((size_t)(b * 8 + head) * SEQ + s) * 64;
; #pragma unroll
.LBB0_149:
	v_cvt_pk_bf16_f32 v83, v76, v77
	v_mov_b32_e32 v76, v111
	v_mov_b32_e32 v77, v112
	v_mov_b32_e32 v111, v113
	v_pk_add_f32 v[76:77], v[76:77], v[110:111]
	v_cvt_pk_bf16_f32 v80, v94, v95
	v_add_f32_e32 v76, v76, v77
	v_fmamk_f32 v76, v76, 0x3c000000, v245
	v_cmp_gt_f32_e32 vcc, s83, v76
	v_mul_f32_e32 v77, 0x4b800000, v76
	v_cvt_pk_bf16_f32 v81, v78, v79
	v_cndmask_b32_e32 v76, v76, v77, vcc
	v_cvt_pk_bf16_f32 v82, v74, v75
	v_subrev_u32_e32 v74, s66, v98
	s_mov_b32 s58, s62
	s_mov_b32 s59, s63
	v_rsq_f32_e32 v76, v76
	buffer_store_dwordx4 v[80:83], v74, s[56:59], 0 offen
	v_ashrrev_i32_e32 v74, 8, v186
	v_readlane_b32 s26, v253, 34
	v_and_b32_e32 v80, -8, v74
	v_add_u32_e32 v74, s21, v80
	v_ashrrev_i32_e32 v75, 31, v74
	v_mul_f32_e32 v77, 0x45800000, v76
	v_lshlrev_b64 v[74:75], 18, v[74:75]
	v_cndmask_b32_e32 v82, v76, v77, vcc
	v_readlane_b32 s27, v253, 35
	v_pk_mul_f32 v[66:67], v[66:67], v[82:83] op_sel_hi:[1,0]
	v_pk_mul_f32 v[68:69], v[68:69], v[82:83] op_sel_hi:[1,0]
	v_pk_mul_f32 v[76:77], v[62:63], v[82:83] op_sel_hi:[1,0]
	v_pk_mul_f32 v[78:79], v[64:65], v[82:83] op_sel_hi:[1,0]
	v_and_b32_e32 v83, 0x7cf, v186
	s_mov_b64 s[2:3], -1
	s_and_b64 vcc, exec, s[44:45]
	v_lshl_add_u64 v[64:65], s[26:27], 0, v[74:75]
	s_cbranch_vccnz .LBB0_151
	v_lshlrev_b32_e32 v62, 7, v83
	v_mov_b32_e32 v63, v1
	v_lshl_add_u64 v[84:85], v[64:65], 0, v[62:63]
	v_or3_b32 v62, v62, v0, v74
	v_lshl_add_u64 v[88:89], v[84:85], 0, v[0:1]
	v_cvt_pk_bf16_f32 v84, v66, v67
	v_cvt_pk_bf16_f32 v85, v68, v69
	v_cvt_pk_bf16_f32 v86, v76, v77
	v_cvt_pk_bf16_f32 v87, v78, v79
	v_add_u32_e32 v62, 0x17a00000, v62
	buffer_store_dwordx4 v[84:87], v62, s[56:59], 0 offen
	s_mov_b64 s[2:3], 0
	s_nop 0
	v_lshl_add_u64 v[84:85], v[88:89], 0, 64
.LBB0_151:
	v_add_u32_e32 v62, s28, v80
	v_ashrrev_i32_e32 v63, 31, v62
	v_lshlrev_b64 v[62:63], 11, v[62:63]
	v_pk_mul_f32 v[80:81], v[58:59], v[82:83] op_sel_hi:[1,0]
	v_pk_mul_f32 v[58:59], v[60:61], v[82:83] op_sel_hi:[1,0]
	v_pk_mul_f32 v[54:55], v[54:55], v[82:83] op_sel_hi:[1,0]
	s_andn2_b64 vcc, exec, s[2:3]
	v_pk_mul_f32 v[56:57], v[56:57], v[82:83] op_sel_hi:[1,0]
	s_cbranch_vccnz .LBB0_153
	v_mov_b64_e32 v[60:61], s[70:71]
	v_mad_i64_i32 v[60:61], s[2:3], v186, s85, v[60:61]
	v_lshl_add_u64 v[60:61], v[60:61], 0, v[0:1]
	v_add_co_u32_e32 v60, vcc, 0x1000, v60
	v_pk_mul_f32 v[88:89], v[68:69], v[68:69]
	s_nop 0
	v_addc_co_u32_e32 v61, vcc, 0, v61, vcc
	global_load_dwordx4 v[84:87], v[60:61], off offset:1792
	global_load_dwordx4 v[94:97], v[170:171], off
	global_load_dwordx4 v[98:101], v[170:171], off offset:16
	v_pk_mul_f32 v[60:61], v[66:67], v[66:67]
	v_pk_mul_f32 v[102:103], v[76:77], v[76:77]
	v_add_f32_e32 v60, v60, v61
	v_add_f32_e32 v60, v88, v60
	v_add_f32_e32 v60, v89, v60
	v_add_f32_e32 v60, v102, v60
	v_pk_mul_f32 v[104:105], v[78:79], v[78:79]
	v_add_f32_e32 v60, v103, v60
	v_add_f32_e32 v60, v104, v60
	v_pk_mul_f32 v[106:107], v[80:81], v[80:81]
	v_add_f32_e32 v60, v105, v60
	v_add_f32_e32 v60, v106, v60
	v_pk_mul_f32 v[108:109], v[58:59], v[58:59]
	v_add_f32_e32 v60, v107, v60
	v_add_f32_e32 v60, v108, v60
	v_pk_mul_f32 v[110:111], v[54:55], v[54:55]
	v_add_f32_e32 v60, v109, v60
	v_add_f32_e32 v60, v110, v60
	v_pk_mul_f32 v[112:113], v[56:57], v[56:57]
	v_add_f32_e32 v60, v111, v60
	v_add_f32_e32 v60, v112, v60
	v_and_b32_e32 v82, 64, v247
	v_add_f32_e32 v110, v113, v60
	v_xor_b32_e32 v75, 16, v247
	v_add_u32_e32 v82, 64, v82
	v_cmp_lt_i32_e32 vcc, v75, v82
	s_movk_i32 s21, 0xc0
	s_mov_b32 s58, s62
	v_cndmask_b32_e32 v61, v247, v75, vcc
	v_lshlrev_b32_e32 v75, 2, v61
	s_mov_b32 s59, s63
	v_readlane_b32 s2, v253, 32
	v_readlane_b32 s3, v253, 33
	s_waitcnt vmcnt(0)
	v_lshlrev_b32_e32 v106, 16, v84
	v_and_b32_e32 v107, 0xffff0000, v84
	v_pk_mul_f32 v[108:109], v[106:107], v[106:107]
	v_lshlrev_b32_e32 v104, 16, v85
	v_and_b32_e32 v105, 0xffff0000, v85
	v_add_f32_e32 v108, v110, v108
	v_and_b32_e32 v88, 0xffff0000, v86
	v_lshlrev_b32_e32 v89, 16, v86
	v_and_b32_e32 v102, 0xffff0000, v87
	v_lshlrev_b32_e32 v103, 16, v87
	v_pk_mul_f32 v[86:87], v[104:105], v[104:105]
	v_add_f32_e32 v108, v109, v108
	v_add_f32_e32 v86, v86, v108
	v_pk_mul_f32 v[60:61], v[88:89], v[88:89]
	v_add_f32_e32 v86, v87, v86
	v_add_f32_e32 v61, v61, v86
	v_pk_mul_f32 v[84:85], v[102:103], v[102:103]
	v_add_f32_e32 v60, v60, v61
	v_add_f32_e32 v60, v85, v60
	v_add_f32_e32 v60, v84, v60
	ds_bpermute_b32 v61, v75, v60
	v_xor_b32_e32 v75, 32, v247
	v_cmp_lt_i32_e32 vcc, v75, v82
	v_or_b32_e32 v109, v62, v83
	v_mul_lo_u32 v82, v109, s21
	v_cndmask_b32_e32 v75, v247, v75, vcc
	v_lshlrev_b32_e32 v75, 2, v75
	s_waitcnt lgkmcnt(0)
	v_add_f32_e32 v60, v60, v61
	ds_bpermute_b32 v61, v75, v60
	v_add_u32_e32 v83, v82, v172
	v_add_u32_e32 v82, v174, v82
	s_waitcnt lgkmcnt(0)
; #define wt16(p, v) wt16b(WSB, (p), (v))
; __device__ __forceinline__ u32x4 pack8(const float (&f)[8]) { u32x4 v; v.x = cvt_pk_bf16(f[0], f[1]); v.y = cvt_pk_bf16(f[2], f[3]); v.z = cvt_pk_bf16(f[4], f[5]); v.w = cvt_pk_bf16(f[6], f[7]); return v; }
;     __device__ __forceinline__ void operator()(const f32x4 (&acc)[2][2][4][2], const pg8::Unit& u, int wr, int wc, int fr, int fq) const {
;     ...
;                     const float rk = rsqrtf(ssn * (1.f / 96.f) + EPS);
;                     bf16_t* kb = Kf + ((size_t)(b * 8 + head) * SEQ + s) * 96;
; #pragma unroll
;                     for (int bj = 0; bj < 2; ++bj) {
;                         float o[8];
; #pragma unroll
;                         for (int e = 0; e < 8; ++e) o[e] = v[bj][e] * rk * khn[32 * bj + 8 * fq + e];
;                         wt16(kb + 32 * bj + 8 * fq, pack8(o));
;                     }
;                     float o[8];
; #pragma unroll
;                     for (int e = 0; e < 8; ++e) {
;                         const float mine = pe[e] * rk * khn[64 + 8 * fq + e];
;                         const float other = __shfl_xor(mine, 32);
;                         const float2 c = cs[(size_t)row * 16 + ((8 * fq + e) & 15)];
;                         o[e] = (fq < 2) ? (mine * c.x - other * c.y) : (other * c.y + mine * c.x);
;                     }
;                     wt16(kb + 64 + 8 * fq, pack8(o));
;                 } else {
;                     const int head = 4 * (pn - 2) + wc;
;                     bf16_t* vb = Vt + ((size_t)(b * 8 + head) * SEQ + s) * 64;
; #pragma unroll
;                     for (int bj = 0; bj < 2; ++bj) wt16(vb + 32 * bj + 8 * fq, pack8(v[bj]));
	v_add_f32_e32 v60, v60, v61
	v_fmamk_f32 v60, v60, 0x3c2aaaab, v245
	v_mul_f32_e32 v61, 0x4b800000, v60
	v_cmp_gt_f32_e32 vcc, s83, v60
	s_nop 1
	v_cndmask_b32_e32 v60, v60, v61, vcc
	v_rsq_f32_e32 v60, v60
	s_nop 0
	v_mul_f32_e32 v61, 0x45800000, v60
	v_cndmask_b32_e32 v108, v60, v61, vcc
	v_pk_mul_f32 v[60:61], v[66:67], v[108:109] op_sel_hi:[1,0]
	v_pk_mul_f32 v[66:67], v[68:69], v[108:109] op_sel_hi:[1,0]
	v_pk_mul_f32 v[68:69], v[76:77], v[108:109] op_sel_hi:[1,0]
	v_pk_mul_f32 v[76:77], v[78:79], v[108:109] op_sel_hi:[1,0]
	v_pk_mul_f32 v[60:61], v[94:95], v[60:61]
	v_pk_mul_f32 v[78:79], v[96:97], v[66:67]
	v_pk_mul_f32 v[68:69], v[98:99], v[68:69]
	v_pk_mul_f32 v[76:77], v[100:101], v[76:77]
	v_cvt_pk_bf16_f32 v66, v60, v61
	v_cvt_pk_bf16_f32 v67, v78, v79
	v_cvt_pk_bf16_f32 v68, v68, v69
	v_cvt_pk_bf16_f32 v69, v76, v77
	buffer_store_dwordx4 v[66:69], v83, s[56:59], 0 offen
	global_load_dwordx4 v[66:69], v[170:171], off offset:128
	s_nop 0
	global_load_dwordx4 v[76:79], v[170:171], off offset:144
	v_lshlrev_b64 v[60:61], 7, v[186:187]
	v_lshl_add_u64 v[84:85], v[168:169], 0, v[60:61]
	v_pk_mul_f32 v[60:61], v[80:81], v[108:109] op_sel_hi:[1,0]
	v_pk_mul_f32 v[58:59], v[58:59], v[108:109] op_sel_hi:[1,0]
	v_pk_mul_f32 v[54:55], v[54:55], v[108:109] op_sel_hi:[1,0]
	v_pk_mul_f32 v[56:57], v[56:57], v[108:109] op_sel_hi:[1,0]
	v_pk_mul_f32 v[96:97], v[108:109], v[106:107] op_sel_hi:[0,1]
	v_pk_mul_f32 v[98:99], v[108:109], v[104:105] op_sel_hi:[0,1]
	v_pk_mul_f32 v[88:89], v[108:109], v[88:89] op_sel_hi:[0,1]
	v_pk_mul_f32 v[100:101], v[108:109], v[102:103] op_sel_hi:[0,1]
	v_mov_b64_e32 v[94:95], s[2:3]
	v_mad_u64_u32 v[94:95], s[2:3], v109, s21, v[94:95]
	v_mad_i32_i24 v95, v63, s21, v95
	v_lshl_add_u64 v[94:95], v[94:95], 0, v[0:1]
	s_waitcnt vmcnt(1)
	v_pk_mul_f32 v[60:61], v[66:67], v[60:61]
	v_pk_mul_f32 v[58:59], v[68:69], v[58:59]
	s_waitcnt vmcnt(0)
	v_pk_mul_f32 v[66:67], v[76:77], v[54:55]
	v_pk_mul_f32 v[68:69], v[78:79], v[56:57]
	v_cvt_pk_bf16_f32 v54, v60, v61
	v_cvt_pk_bf16_f32 v55, v58, v59
	v_cvt_pk_bf16_f32 v56, v66, v67
	v_cvt_pk_bf16_f32 v57, v68, v69
	buffer_store_dwordx4 v[54:57], v82, s[56:59], 0 offen
	global_load_dwordx4 v[54:57], v[170:171], off offset:256
	s_nop 0
	global_load_dwordx4 v[58:61], v[84:85], off
	global_load_dwordx4 v[66:69], v[84:85], off offset:16
	global_load_dwordx4 v[76:79], v[170:171], off offset:272
	global_load_dwordx4 v[80:83], v[84:85], off offset:32
	s_nop 0
	global_load_dwordx4 v[84:87], v[84:85], off offset:48
	s_waitcnt vmcnt(5)
	v_pk_mul_f32 v[54:55], v[96:97], v[54:55]
	s_waitcnt vmcnt(4)
	v_mov_b32_e32 v96, v58
	v_mov_b32_e32 v97, v60
	v_mov_b32_e32 v60, v59
	v_pk_mul_f32 v[56:57], v[98:99], v[56:57]
	s_waitcnt vmcnt(3)
	v_mov_b32_e32 v58, v66
	v_mov_b32_e32 v59, v68
	v_mov_b32_e32 v68, v67
	s_waitcnt vmcnt(2)
	v_pk_mul_f32 v[66:67], v[88:89], v[76:77] op_sel:[1,0] op_sel_hi:[0,1]
	v_pk_mul_f32 v[78:79], v[100:101], v[78:79] op_sel:[1,0] op_sel_hi:[0,1]
	s_waitcnt vmcnt(1)
	v_mov_b32_e32 v76, v80
	v_mov_b32_e32 v77, v82
	v_mov_b32_e32 v82, v81
	ds_bpermute_b32 v80, v75, v54
	ds_bpermute_b32 v81, v75, v55
	ds_bpermute_b32 v98, v75, v56
	ds_bpermute_b32 v99, v75, v57
	ds_bpermute_b32 v100, v75, v66
	ds_bpermute_b32 v101, v75, v67
	ds_bpermute_b32 v102, v75, v78
	ds_bpermute_b32 v103, v75, v79
	s_waitcnt vmcnt(0)
	v_mov_b32_e32 v89, v86
	v_mov_b32_e32 v86, v85
	s_waitcnt lgkmcnt(6)
	v_pk_mul_f32 v[60:61], v[60:61], v[80:81]
	s_waitcnt lgkmcnt(4)
	v_pk_mul_f32 v[68:69], v[68:69], v[98:99]
	s_waitcnt lgkmcnt(2)
	v_pk_mul_f32 v[80:81], v[82:83], v[100:101]
	s_waitcnt lgkmcnt(0)
	v_pk_mul_f32 v[82:83], v[86:87], v[102:103]
	v_mov_b32_e32 v88, v84
	v_cndmask_b32_e64 v61, v61, -v61, s[40:41]
	v_cndmask_b32_e64 v60, v60, -v60, s[40:41]
	v_cndmask_b32_e64 v69, v69, -v69, s[40:41]
	v_cndmask_b32_e64 v68, v68, -v68, s[40:41]
	v_cndmask_b32_e64 v85, v81, -v81, s[40:41]
	v_cndmask_b32_e64 v84, v80, -v80, s[40:41]
	v_cndmask_b32_e64 v83, v83, -v83, s[40:41]
	v_cndmask_b32_e64 v82, v82, -v82, s[40:41]
	v_pk_fma_f32 v[80:81], v[54:55], v[96:97], v[60:61]
	v_pk_fma_f32 v[58:59], v[56:57], v[58:59], v[68:69]
	v_pk_fma_f32 v[54:55], v[66:67], v[76:77], v[84:85]
	v_pk_fma_f32 v[56:57], v[78:79], v[88:89], v[82:83]
	v_lshl_add_u64 v[84:85], v[94:95], 0, s[80:81]
.LBB0_153:
	v_cvt_pk_bf16_f32 v68, v54, v55
	v_mov_b32_e32 v54, v91
	v_mov_b32_e32 v55, v92
	v_mov_b32_e32 v91, v93
	v_pk_add_f32 v[54:55], v[54:55], v[90:91]
	v_cvt_pk_bf16_f32 v66, v80, v81
	v_add_f32_e32 v54, v54, v55
	v_fmamk_f32 v54, v54, 0x3c000000, v245
	v_mul_f32_e32 v55, 0x4b800000, v54
	v_cmp_gt_f32_e32 vcc, s83, v54
	v_cvt_pk_bf16_f32 v67, v58, v59
	v_cvt_pk_bf16_f32 v69, v56, v57
	v_cndmask_b32_e32 v54, v54, v55, vcc
	v_rsq_f32_e32 v54, v54
	v_subrev_u32_e32 v56, s66, v84
	s_mov_b32 s58, s62
	s_mov_b32 s59, s63
	v_mul_f32_e32 v55, 0x45800000, v54
	buffer_store_dwordx4 v[66:69], v56, s[56:59], 0 offen
	v_cndmask_b32_e32 v56, v54, v55, vcc
	v_pk_mul_f32 v[46:47], v[46:47], v[56:57] op_sel_hi:[1,0]
	v_pk_mul_f32 v[48:49], v[48:49], v[56:57] op_sel_hi:[1,0]
	v_pk_mul_f32 v[54:55], v[42:43], v[56:57] op_sel_hi:[1,0]
	v_pk_mul_f32 v[44:45], v[44:45], v[56:57] op_sel_hi:[1,0]
	v_and_b32_e32 v57, 0x7df, v184
	s_and_b64 vcc, exec, s[44:45]
	s_mov_b64 s[2:3], -1
	s_cbranch_vccnz .LBB0_155
	v_lshlrev_b32_e32 v42, 7, v57
	v_mov_b32_e32 v43, v1
	v_lshl_add_u64 v[58:59], v[64:65], 0, v[42:43]
	v_or3_b32 v42, v42, v0, v74
	v_lshl_add_u64 v[66:67], v[58:59], 0, v[0:1]
	v_cvt_pk_bf16_f32 v58, v46, v47
	v_cvt_pk_bf16_f32 v59, v48, v49
	v_cvt_pk_bf16_f32 v60, v54, v55
	v_cvt_pk_bf16_f32 v61, v44, v45
	v_add_u32_e32 v42, 0x17a00000, v42
	buffer_store_dwordx4 v[58:61], v42, s[56:59], 0 offen
	s_mov_b64 s[2:3], 0
	s_nop 0
	v_lshl_add_u64 v[58:59], v[66:67], 0, 64
; #define wt16(p, v) wt16b(WSB, (p), (v))
; __device__ __forceinline__ u32x4 pack8(const float (&f)[8]) { u32x4 v; v.x = cvt_pk_bf16(f[0], f[1]); v.y = cvt_pk_bf16(f[2], f[3]); v.z = cvt_pk_bf16(f[4], f[5]); v.w = cvt_pk_bf16(f[6], f[7]); return v; }
;     __device__ __forceinline__ void operator()(const f32x4 (&acc)[2][2][4][2], const pg8::Unit& u, int wr, int wc, int fr, int fq) const {
;     ...
;                 if (pn < 2) {
;                     const int head = 4 * pn + wc;
;                     float ssn = 0.f;
; #pragma unroll
;                     for (int bj = 0; bj < 2; ++bj)
; #pragma unroll
;                         for (int e = 0; e < 8; ++e) ssn += v[bj][e] * v[bj][e];
;                     float pe[8]; unpack8(*(const u32x4*)(U + (size_t)row * NU + UPE + 8 * fq), pe);
; #pragma unroll
;                     for (int e = 0; e < 8; ++e) ssn += pe[e] * pe[e];
;                     ssn += __shfl_xor(ssn, 16); ssn += __shfl_xor(ssn, 32);
;                     const float rk = rsqrtf(ssn * (1.f / 96.f) + EPS);
;                     bf16_t* kb = Kf + ((size_t)(b * 8 + head) * SEQ + s) * 96;
; #pragma unroll
;                     for (int bj = 0; bj < 2; ++bj) {
;                         float o[8];
; #pragma unroll
;                         for (int e = 0; e < 8; ++e) o[e] = v[bj][e] * rk * khn[32 * bj + 8 * fq + e];
;                         wt16(kb + 32 * bj + 8 * fq, pack8(o));
;                     }
;                     float o[8];
; #pragma unroll
;                     for (int e = 0; e < 8; ++e) {
;                         const float mine = pe[e] * rk * khn[64 + 8 * fq + e];
;                         const float other = __shfl_xor(mine, 32);
.LBB0_155:
	v_pk_mul_f32 v[42:43], v[38:39], v[56:57] op_sel_hi:[1,0]
	v_pk_mul_f32 v[38:39], v[40:41], v[56:57] op_sel_hi:[1,0]
	v_pk_mul_f32 v[34:35], v[34:35], v[56:57] op_sel_hi:[1,0]
	s_andn2_b64 vcc, exec, s[2:3]
	v_pk_mul_f32 v[36:37], v[36:37], v[56:57] op_sel_hi:[1,0]
	s_cbranch_vccnz .LBB0_157
	v_mov_b64_e32 v[40:41], s[70:71]
	v_mad_i64_i32 v[40:41], s[2:3], v184, s85, v[40:41]
	v_lshl_add_u64 v[40:41], v[40:41], 0, v[0:1]
	v_add_co_u32_e32 v40, vcc, 0x1000, v40
	v_pk_mul_f32 v[80:81], v[48:49], v[48:49]
	s_nop 0
	v_addc_co_u32_e32 v41, vcc, 0, v41, vcc
	global_load_dwordx4 v[58:61], v[40:41], off offset:1792
	global_load_dwordx4 v[66:69], v[170:171], off
	global_load_dwordx4 v[76:79], v[170:171], off offset:16
	v_pk_mul_f32 v[40:41], v[46:47], v[46:47]
	v_pk_mul_f32 v[82:83], v[54:55], v[54:55]
	v_add_f32_e32 v40, v40, v41
	v_add_f32_e32 v40, v80, v40
	v_add_f32_e32 v40, v81, v40
	v_add_f32_e32 v40, v82, v40
	v_pk_mul_f32 v[84:85], v[44:45], v[44:45]
	v_add_f32_e32 v40, v83, v40
	v_add_f32_e32 v40, v84, v40
	v_pk_mul_f32 v[86:87], v[42:43], v[42:43]
	v_add_f32_e32 v40, v85, v40
	v_add_f32_e32 v40, v86, v40
	v_pk_mul_f32 v[88:89], v[38:39], v[38:39]
	v_add_f32_e32 v40, v87, v40
	v_add_f32_e32 v40, v88, v40
	v_pk_mul_f32 v[90:91], v[34:35], v[34:35]
	v_add_f32_e32 v40, v89, v40
	v_add_f32_e32 v40, v90, v40
	v_pk_mul_f32 v[92:93], v[36:37], v[36:37]
	v_add_f32_e32 v40, v91, v40
	v_add_f32_e32 v40, v92, v40
	v_and_b32_e32 v75, 64, v247
	v_add_f32_e32 v90, v93, v40
	v_xor_b32_e32 v56, 16, v247
	v_add_u32_e32 v75, 64, v75
	v_cmp_lt_i32_e32 vcc, v56, v75
	s_movk_i32 s21, 0xc0
	s_mov_b32 s58, s62
	v_cndmask_b32_e32 v41, v247, v56, vcc
	v_lshlrev_b32_e32 v56, 2, v41
	s_mov_b32 s59, s63
	v_readlane_b32 s2, v253, 32
	v_readlane_b32 s3, v253, 33
	s_waitcnt vmcnt(0)
	v_lshlrev_b32_e32 v86, 16, v58
	v_and_b32_e32 v87, 0xffff0000, v58
	v_pk_mul_f32 v[88:89], v[86:87], v[86:87]
	v_lshlrev_b32_e32 v84, 16, v59
	v_and_b32_e32 v85, 0xffff0000, v59
	v_add_f32_e32 v88, v90, v88
	v_and_b32_e32 v80, 0xffff0000, v60
	v_lshlrev_b32_e32 v81, 16, v60
	v_and_b32_e32 v82, 0xffff0000, v61
	v_lshlrev_b32_e32 v83, 16, v61
	v_pk_mul_f32 v[60:61], v[84:85], v[84:85]
	v_add_f32_e32 v88, v89, v88
	v_add_f32_e32 v60, v60, v88
	v_pk_mul_f32 v[40:41], v[80:81], v[80:81]
	v_add_f32_e32 v60, v61, v60
	v_add_f32_e32 v41, v41, v60
	v_pk_mul_f32 v[58:59], v[82:83], v[82:83]
	v_add_f32_e32 v40, v40, v41
	v_add_f32_e32 v40, v59, v40
	v_add_f32_e32 v40, v58, v40
	ds_bpermute_b32 v41, v56, v40
	v_xor_b32_e32 v56, 32, v247
	v_cmp_lt_i32_e32 vcc, v56, v75
	v_or_b32_e32 v89, v62, v57
	v_mul_lo_u32 v60, v89, s21
	v_cndmask_b32_e32 v56, v247, v56, vcc
	v_lshlrev_b32_e32 v75, 2, v56
	s_waitcnt lgkmcnt(0)
	v_add_f32_e32 v40, v40, v41
	ds_bpermute_b32 v41, v75, v40
	v_add_u32_e32 v56, v60, v172
	s_waitcnt lgkmcnt(0)
	v_add_f32_e32 v40, v40, v41
	v_fmamk_f32 v40, v40, 0x3c2aaaab, v245
	v_mul_f32_e32 v41, 0x4b800000, v40
	v_cmp_gt_f32_e32 vcc, s83, v40
	s_nop 1
	v_cndmask_b32_e32 v40, v40, v41, vcc
	v_rsq_f32_e32 v40, v40
	s_nop 0
	v_mul_f32_e32 v41, 0x45800000, v40
	v_cndmask_b32_e32 v88, v40, v41, vcc
	v_pk_mul_f32 v[40:41], v[46:47], v[88:89] op_sel_hi:[1,0]
	v_pk_mul_f32 v[46:47], v[48:49], v[88:89] op_sel_hi:[1,0]
	v_pk_mul_f32 v[48:49], v[54:55], v[88:89] op_sel_hi:[1,0]
	v_pk_mul_f32 v[44:45], v[44:45], v[88:89] op_sel_hi:[1,0]
	v_pk_mul_f32 v[40:41], v[66:67], v[40:41]
	v_pk_mul_f32 v[46:47], v[68:69], v[46:47]
	v_pk_mul_f32 v[48:49], v[76:77], v[48:49]
	v_pk_mul_f32 v[54:55], v[78:79], v[44:45]
	v_cvt_pk_bf16_f32 v44, v40, v41
	v_cvt_pk_bf16_f32 v45, v46, v47
	v_cvt_pk_bf16_f32 v46, v48, v49
	v_cvt_pk_bf16_f32 v47, v54, v55
	buffer_store_dwordx4 v[44:47], v56, s[56:59], 0 offen
	global_load_dwordx4 v[44:47], v[170:171], off offset:128
	s_nop 0
	global_load_dwordx4 v[54:57], v[170:171], off offset:144
	v_lshlrev_b64 v[40:41], 7, v[184:185]
	v_lshl_add_u64 v[58:59], v[168:169], 0, v[40:41]
	v_pk_mul_f32 v[40:41], v[42:43], v[88:89] op_sel_hi:[1,0]
	v_pk_mul_f32 v[38:39], v[38:39], v[88:89] op_sel_hi:[1,0]
	v_pk_mul_f32 v[34:35], v[34:35], v[88:89] op_sel_hi:[1,0]
	v_pk_mul_f32 v[36:37], v[36:37], v[88:89] op_sel_hi:[1,0]
	v_add_u32_e32 v48, v174, v60
	v_pk_mul_f32 v[68:69], v[88:89], v[86:87] op_sel_hi:[0,1]
	v_pk_mul_f32 v[76:77], v[88:89], v[84:85] op_sel_hi:[0,1]
	v_pk_mul_f32 v[78:79], v[88:89], v[80:81] op_sel_hi:[0,1]
	v_pk_mul_f32 v[80:81], v[88:89], v[82:83] op_sel_hi:[0,1]
	v_mov_b64_e32 v[66:67], s[2:3]
	v_mad_u64_u32 v[66:67], s[2:3], v89, s21, v[66:67]
	v_mad_i32_i24 v67, v63, s21, v67
	v_lshl_add_u64 v[66:67], v[66:67], 0, v[0:1]
	s_waitcnt vmcnt(1)
	v_pk_mul_f32 v[40:41], v[44:45], v[40:41]
	v_pk_mul_f32 v[38:39], v[46:47], v[38:39]
	s_waitcnt vmcnt(0)
	v_pk_mul_f32 v[42:43], v[54:55], v[34:35]
	v_pk_mul_f32 v[44:45], v[56:57], v[36:37]
	v_cvt_pk_bf16_f32 v34, v40, v41
	v_cvt_pk_bf16_f32 v35, v38, v39
	v_cvt_pk_bf16_f32 v36, v42, v43
	v_cvt_pk_bf16_f32 v37, v44, v45
	buffer_store_dwordx4 v[34:37], v48, s[56:59], 0 offen
	global_load_dwordx4 v[34:37], v[170:171], off offset:256
	s_nop 0
	global_load_dwordx4 v[38:41], v[58:59], off
	global_load_dwordx4 v[42:45], v[58:59], off offset:16
	global_load_dwordx4 v[46:49], v[170:171], off offset:272
	global_load_dwordx4 v[54:57], v[58:59], off offset:32
	s_nop 0
	global_load_dwordx4 v[58:61], v[58:59], off offset:48
	s_waitcnt vmcnt(5)
	v_pk_mul_f32 v[34:35], v[68:69], v[34:35]
	v_pk_mul_f32 v[36:37], v[76:77], v[36:37]
	s_waitcnt vmcnt(4)
	v_mov_b32_e32 v68, v38
	s_waitcnt vmcnt(2)
; #define wt16(p, v) wt16b(WSB, (p), (v))
;     __device__ __forceinline__ void operator()(const f32x4 (&acc)[2][2][4][2], const pg8::Unit& u, int wr, int wc, int fr, int fq) const {
;     ...
;                 const int row = row0 + ai * 128 + m * 16; const float rkv = rsqrtf(sum4q(rq[ai][m]) * (1.f / 128.f) + EPS);
;                 const int b = row >> 11, s = row & (SEQ - 1);
;                 float v[2][8];
; #pragma unroll
;                 for (int bj = 0; bj < 2; ++bj)
; #pragma unroll
;                     for (int n = 0; n < 2; ++n)
; #pragma unroll
;                         for (int i = 0; i < 4; ++i) v[bj][4 * n + i] = acc[ai][bj][m][n][i] * rkv;
;                 if (pn < 2) {
;                     const int head = 4 * pn + wc;
;                     float ssn = 0.f;
; #pragma unroll
;                     for (int bj = 0; bj < 2; ++bj)
; #pragma unroll
;                         for (int e = 0; e < 8; ++e) ssn += v[bj][e] * v[bj][e];
;                     float pe[8]; unpack8(*(const u32x4*)(U + (size_t)row * NU + UPE + 8 * fq), pe);
; #pragma unroll
;                     for (int e = 0; e < 8; ++e) ssn += pe[e] * pe[e];
;                     ssn += __shfl_xor(ssn, 16); ssn += __shfl_xor(ssn, 32);
;                     const float rk = rsqrtf(ssn * (1.f / 96.f) + EPS);
;                     bf16_t* kb = Kf + ((size_t)(b * 8 + head) * SEQ + s) * 96;
; #pragma unroll
;                     for (int bj = 0; bj < 2; ++bj) {
;                         float o[8];
; #pragma unroll
;                         for (int e = 0; e < 8; ++e) o[e] = v[bj][e] * rk * khn[32 * bj + 8 * fq + e];
;                         wt16(kb + 32 * bj + 8 * fq, pack8(o));
;                     }
;                     float o[8];
; #pragma unroll
;                     for (int e = 0; e < 8; ++e) {
;                         const float mine = pe[e] * rk * khn[64 + 8 * fq + e];
;                         const float other = __shfl_xor(mine, 32);
;                         const float2 c = cs[(size_t)row * 16 + ((8 * fq + e) & 15)];
;                         o[e] = (fq < 2) ? (mine * c.x - other * c.y) : (other * c.y + mine * c.x);
;                     }
;                     wt16(kb + 64 + 8 * fq, pack8(o));
;                 } else {
;                     const int head = 4 * (pn - 2) + wc;
;                     bf16_t* vb = Vt + ((size_t)(b * 8 + head) * SEQ + s) * 64;
; #pragma unroll
	v_pk_mul_f32 v[46:47], v[78:79], v[46:47] op_sel:[1,0] op_sel_hi:[0,1]
	v_pk_mul_f32 v[48:49], v[80:81], v[48:49] op_sel:[1,0] op_sel_hi:[0,1]
	v_mov_b32_e32 v69, v40
	v_mov_b32_e32 v40, v39
	v_mov_b32_e32 v38, v42
	v_mov_b32_e32 v39, v44
	v_mov_b32_e32 v44, v43
	ds_bpermute_b32 v42, v75, v34
	ds_bpermute_b32 v43, v75, v35
	ds_bpermute_b32 v78, v75, v36
	ds_bpermute_b32 v79, v75, v37
	ds_bpermute_b32 v80, v75, v46
	ds_bpermute_b32 v81, v75, v47
	ds_bpermute_b32 v82, v75, v48
	ds_bpermute_b32 v83, v75, v49
	s_waitcnt vmcnt(1)
	v_mov_b32_e32 v77, v56
	v_mov_b32_e32 v56, v55
	s_waitcnt vmcnt(0)
	v_mov_b32_e32 v55, v60
	v_mov_b32_e32 v60, v59
	s_waitcnt lgkmcnt(6)
	v_pk_mul_f32 v[40:41], v[40:41], v[42:43]
	s_waitcnt lgkmcnt(4)
	v_pk_mul_f32 v[42:43], v[44:45], v[78:79]
	s_waitcnt lgkmcnt(2)
	v_pk_mul_f32 v[44:45], v[56:57], v[80:81]
	s_waitcnt lgkmcnt(0)
	v_pk_mul_f32 v[56:57], v[60:61], v[82:83]
	v_mov_b32_e32 v76, v54
	v_mov_b32_e32 v54, v58
	v_cndmask_b32_e64 v41, v41, -v41, s[40:41]
	v_cndmask_b32_e64 v40, v40, -v40, s[40:41]
	v_cndmask_b32_e64 v59, v43, -v43, s[40:41]
	v_cndmask_b32_e64 v58, v42, -v42, s[40:41]
	v_cndmask_b32_e64 v45, v45, -v45, s[40:41]
	v_cndmask_b32_e64 v44, v44, -v44, s[40:41]
	v_cndmask_b32_e64 v57, v57, -v57, s[40:41]
	v_cndmask_b32_e64 v56, v56, -v56, s[40:41]
	v_pk_fma_f32 v[42:43], v[34:35], v[68:69], v[40:41]
	v_pk_fma_f32 v[38:39], v[36:37], v[38:39], v[58:59]
	v_pk_fma_f32 v[34:35], v[46:47], v[76:77], v[44:45]
	v_pk_fma_f32 v[36:37], v[48:49], v[54:55], v[56:57]
	v_lshl_add_u64 v[58:59], v[66:67], 0, s[80:81]
.LBB0_157:
	v_cvt_pk_bf16_f32 v40, v42, v43
	v_cvt_pk_bf16_f32 v42, v34, v35
	v_mov_b32_e32 v34, v71
	v_mov_b32_e32 v35, v72
	v_mov_b32_e32 v71, v73
	v_pk_add_f32 v[34:35], v[34:35], v[70:71]
	v_cvt_pk_bf16_f32 v41, v38, v39
	v_add_f32_e32 v34, v34, v35
	v_fmamk_f32 v34, v34, 0x3c000000, v245
	v_mul_f32_e32 v35, 0x4b800000, v34
	v_cmp_gt_f32_e32 vcc, s83, v34
	v_cvt_pk_bf16_f32 v43, v36, v37
	v_subrev_u32_e32 v36, s66, v58
	v_cndmask_b32_e32 v34, v34, v35, vcc
	v_rsq_f32_e32 v34, v34
	s_mov_b32 s58, s62
	s_mov_b32 s59, s63
	buffer_store_dwordx4 v[40:43], v36, s[56:59], 0 offen
	v_mul_f32_e32 v35, 0x45800000, v34
	v_cndmask_b32_e32 v36, v34, v35, vcc
	v_pk_mul_f32 v[30:31], v[30:31], v[36:37] op_sel_hi:[1,0]
	v_pk_mul_f32 v[32:33], v[32:33], v[36:37] op_sel_hi:[1,0]
	v_pk_mul_f32 v[34:35], v[26:27], v[36:37] op_sel_hi:[1,0]
	v_pk_mul_f32 v[28:29], v[28:29], v[36:37] op_sel_hi:[1,0]
	v_and_b32_e32 v37, 0x7ef, v182
	s_and_b64 vcc, exec, s[44:45]
	s_mov_b64 s[2:3], -1
	s_cbranch_vccnz .LBB0_159
	v_lshlrev_b32_e32 v26, 7, v37
	v_mov_b32_e32 v27, v1
	v_lshl_add_u64 v[38:39], v[64:65], 0, v[26:27]
	v_or3_b32 v26, v26, v0, v74
	v_lshl_add_u64 v[42:43], v[38:39], 0, v[0:1]
	v_cvt_pk_bf16_f32 v38, v30, v31
	v_cvt_pk_bf16_f32 v39, v32, v33
	v_cvt_pk_bf16_f32 v40, v34, v35
	v_cvt_pk_bf16_f32 v41, v28, v29
	v_add_u32_e32 v26, 0x17a00000, v26
	buffer_store_dwordx4 v[38:41], v26, s[56:59], 0 offen
	s_mov_b64 s[2:3], 0
	s_nop 0
	v_lshl_add_u64 v[38:39], v[42:43], 0, 64
.LBB0_159:
	v_pk_mul_f32 v[26:27], v[22:23], v[36:37] op_sel_hi:[1,0]
	v_pk_mul_f32 v[22:23], v[24:25], v[36:37] op_sel_hi:[1,0]
	v_pk_mul_f32 v[18:19], v[18:19], v[36:37] op_sel_hi:[1,0]
	s_andn2_b64 vcc, exec, s[2:3]
	v_pk_mul_f32 v[20:21], v[20:21], v[36:37] op_sel_hi:[1,0]
	s_cbranch_vccnz .LBB0_161
	v_mov_b64_e32 v[24:25], s[70:71]
	v_mad_i64_i32 v[24:25], s[2:3], v182, s85, v[24:25]
	v_lshl_add_u64 v[24:25], v[24:25], 0, v[0:1]
	v_add_co_u32_e32 v24, vcc, 0x1000, v24
	v_pk_mul_f32 v[54:55], v[32:33], v[32:33]
	s_nop 0
	v_addc_co_u32_e32 v25, vcc, 0, v25, vcc
	global_load_dwordx4 v[38:41], v[24:25], off offset:1792
	global_load_dwordx4 v[42:45], v[170:171], off
	global_load_dwordx4 v[46:49], v[170:171], off offset:16
	v_pk_mul_f32 v[24:25], v[30:31], v[30:31]
	v_pk_mul_f32 v[56:57], v[34:35], v[34:35]
	v_add_f32_e32 v24, v24, v25
	v_add_f32_e32 v24, v54, v24
	v_add_f32_e32 v24, v55, v24
	v_add_f32_e32 v24, v56, v24
	v_pk_mul_f32 v[58:59], v[28:29], v[28:29]
	v_add_f32_e32 v24, v57, v24
	v_add_f32_e32 v24, v58, v24
	v_pk_mul_f32 v[60:61], v[26:27], v[26:27]
	v_add_f32_e32 v24, v59, v24
	v_add_f32_e32 v24, v60, v24
	v_pk_mul_f32 v[66:67], v[22:23], v[22:23]
	v_add_f32_e32 v24, v61, v24
	v_add_f32_e32 v24, v66, v24
	v_pk_mul_f32 v[68:69], v[18:19], v[18:19]
	v_add_f32_e32 v24, v67, v24
	v_add_f32_e32 v24, v68, v24
	v_pk_mul_f32 v[70:71], v[20:21], v[20:21]
	v_add_f32_e32 v24, v69, v24
	v_add_f32_e32 v24, v70, v24
	v_and_b32_e32 v72, 64, v247
	v_add_f32_e32 v68, v71, v24
	v_xor_b32_e32 v36, 16, v247
	v_add_u32_e32 v72, 64, v72
	v_cmp_lt_i32_e32 vcc, v36, v72
	s_movk_i32 s21, 0xc0
	s_mov_b32 s58, s62
	v_cndmask_b32_e32 v25, v247, v36, vcc
	v_lshlrev_b32_e32 v36, 2, v25
	s_mov_b32 s59, s63
	v_readlane_b32 s2, v253, 32
	v_readlane_b32 s3, v253, 33
	s_waitcnt vmcnt(0)
	v_lshlrev_b32_e32 v60, 16, v38
	v_and_b32_e32 v61, 0xffff0000, v38
	v_pk_mul_f32 v[66:67], v[60:61], v[60:61]
	v_lshlrev_b32_e32 v58, 16, v39
	v_and_b32_e32 v59, 0xffff0000, v39
	v_add_f32_e32 v66, v68, v66
	v_and_b32_e32 v54, 0xffff0000, v40
	v_lshlrev_b32_e32 v55, 16, v40
	v_and_b32_e32 v56, 0xffff0000, v41
	v_lshlrev_b32_e32 v57, 16, v41
	v_pk_mul_f32 v[40:41], v[58:59], v[58:59]
	v_add_f32_e32 v66, v67, v66
	v_add_f32_e32 v40, v40, v66
	v_pk_mul_f32 v[24:25], v[54:55], v[54:55]
	v_add_f32_e32 v40, v41, v40
	v_add_f32_e32 v25, v25, v40
	v_pk_mul_f32 v[38:39], v[56:57], v[56:57]
	v_add_f32_e32 v24, v24, v25
	v_add_f32_e32 v24, v39, v24
	v_add_f32_e32 v24, v38, v24
	ds_bpermute_b32 v25, v36, v24
	v_xor_b32_e32 v36, 32, v247
	v_cmp_lt_i32_e32 vcc, v36, v72
	v_or_b32_e32 v68, v62, v37
	s_waitcnt lgkmcnt(0)
; #define wt16(p, v) wt16b(WSB, (p), (v))
; __device__ __forceinline__ u32x4 pack8(const float (&f)[8]) { u32x4 v; v.x = cvt_pk_bf16(f[0], f[1]); v.y = cvt_pk_bf16(f[2], f[3]); v.z = cvt_pk_bf16(f[4], f[5]); v.w = cvt_pk_bf16(f[6], f[7]); return v; }
;     __device__ __forceinline__ void operator()(const f32x4 (&acc)[2][2][4][2], const pg8::Unit& u, int wr, int wc, int fr, int fq) const {
;     ...
;                     ssn += __shfl_xor(ssn, 16); ssn += __shfl_xor(ssn, 32);
;                     const float rk = rsqrtf(ssn * (1.f / 96.f) + EPS);
;                     bf16_t* kb = Kf + ((size_t)(b * 8 + head) * SEQ + s) * 96;
; #pragma unroll
;                     for (int bj = 0; bj < 2; ++bj) {
;                         float o[8];
; #pragma unroll
;                         for (int e = 0; e < 8; ++e) o[e] = v[bj][e] * rk * khn[32 * bj + 8 * fq + e];
;                         wt16(kb + 32 * bj + 8 * fq, pack8(o));
;                     }
;                     float o[8];
; #pragma unroll
;                     for (int e = 0; e < 8; ++e) {
;                         const float mine = pe[e] * rk * khn[64 + 8 * fq + e];
;                         const float other = __shfl_xor(mine, 32);
;                         const float2 c = cs[(size_t)row * 16 + ((8 * fq + e) & 15)];
;                         o[e] = (fq < 2) ? (mine * c.x - other * c.y) : (other * c.y + mine * c.x);
;                     }
;                     wt16(kb + 64 + 8 * fq, pack8(o));
;                 } else {
;                     const int head = 4 * (pn - 2) + wc;
;                     bf16_t* vb = Vt + ((size_t)(b * 8 + head) * SEQ + s) * 64;
; #pragma unroll
;                     for (int bj = 0; bj < 2; ++bj) wt16(vb + 32 * bj + 8 * fq, pack8(v[bj]));
	v_add_f32_e32 v24, v24, v25
	v_cndmask_b32_e32 v36, v247, v36, vcc
	v_lshlrev_b32_e32 v67, 2, v36
	ds_bpermute_b32 v25, v67, v24
	v_mul_lo_u32 v36, v68, s21
	v_add_u32_e32 v37, v36, v172
	v_add_u32_e32 v36, v174, v36
	s_waitcnt lgkmcnt(0)
	v_add_f32_e32 v24, v24, v25
	v_fmamk_f32 v24, v24, 0x3c2aaaab, v245
	v_mul_f32_e32 v25, 0x4b800000, v24
	v_cmp_gt_f32_e32 vcc, s83, v24
	s_nop 1
	v_cndmask_b32_e32 v24, v24, v25, vcc
	v_rsq_f32_e32 v24, v24
	s_nop 0
	v_mul_f32_e32 v25, 0x45800000, v24
	v_cndmask_b32_e32 v66, v24, v25, vcc
	v_pk_mul_f32 v[24:25], v[30:31], v[66:67] op_sel_hi:[1,0]
	v_pk_mul_f32 v[30:31], v[32:33], v[66:67] op_sel_hi:[1,0]
	v_pk_mul_f32 v[32:33], v[34:35], v[66:67] op_sel_hi:[1,0]
	v_pk_mul_f32 v[28:29], v[28:29], v[66:67] op_sel_hi:[1,0]
	v_pk_mul_f32 v[24:25], v[42:43], v[24:25]
	v_pk_mul_f32 v[30:31], v[44:45], v[30:31]
	v_pk_mul_f32 v[32:33], v[46:47], v[32:33]
	v_pk_mul_f32 v[34:35], v[48:49], v[28:29]
	v_cvt_pk_bf16_f32 v28, v24, v25
	v_cvt_pk_bf16_f32 v29, v30, v31
	v_cvt_pk_bf16_f32 v30, v32, v33
	v_cvt_pk_bf16_f32 v31, v34, v35
	buffer_store_dwordx4 v[28:31], v37, s[56:59], 0 offen
	global_load_dwordx4 v[28:31], v[170:171], off offset:128
	s_nop 0
	global_load_dwordx4 v[32:35], v[170:171], off offset:144
	v_lshlrev_b64 v[24:25], 7, v[182:183]
	v_lshl_add_u64 v[38:39], v[168:169], 0, v[24:25]
	v_pk_mul_f32 v[24:25], v[26:27], v[66:67] op_sel_hi:[1,0]
	v_pk_mul_f32 v[22:23], v[22:23], v[66:67] op_sel_hi:[1,0]
	v_pk_mul_f32 v[18:19], v[18:19], v[66:67] op_sel_hi:[1,0]
	v_pk_mul_f32 v[20:21], v[20:21], v[66:67] op_sel_hi:[1,0]
	v_pk_mul_f32 v[44:45], v[66:67], v[60:61] op_sel_hi:[0,1]
	v_pk_mul_f32 v[46:47], v[66:67], v[58:59] op_sel_hi:[0,1]
	v_pk_mul_f32 v[48:49], v[66:67], v[54:55] op_sel_hi:[0,1]
	v_pk_mul_f32 v[54:55], v[66:67], v[56:57] op_sel_hi:[0,1]
	v_mov_b64_e32 v[42:43], s[2:3]
	v_mad_u64_u32 v[42:43], s[2:3], v68, s21, v[42:43]
	v_mad_i32_i24 v43, v63, s21, v43
	v_lshl_add_u64 v[42:43], v[42:43], 0, v[0:1]
	s_waitcnt vmcnt(1)
	v_pk_mul_f32 v[24:25], v[28:29], v[24:25]
	v_pk_mul_f32 v[22:23], v[30:31], v[22:23]
	s_waitcnt vmcnt(0)
	v_pk_mul_f32 v[26:27], v[32:33], v[18:19]
	v_pk_mul_f32 v[28:29], v[34:35], v[20:21]
	v_cvt_pk_bf16_f32 v18, v24, v25
	v_cvt_pk_bf16_f32 v19, v22, v23
	v_cvt_pk_bf16_f32 v20, v26, v27
	v_cvt_pk_bf16_f32 v21, v28, v29
	buffer_store_dwordx4 v[18:21], v36, s[56:59], 0 offen
	global_load_dwordx4 v[18:21], v[170:171], off offset:256
	s_nop 0
	global_load_dwordx4 v[22:25], v[38:39], off
	global_load_dwordx4 v[26:29], v[38:39], off offset:16
	global_load_dwordx4 v[30:33], v[170:171], off offset:272
	global_load_dwordx4 v[34:37], v[38:39], off offset:32
	s_nop 0
	global_load_dwordx4 v[38:41], v[38:39], off offset:48
	s_waitcnt vmcnt(5)
	v_pk_mul_f32 v[18:19], v[44:45], v[18:19]
	v_pk_mul_f32 v[20:21], v[46:47], v[20:21]
	s_waitcnt vmcnt(4)
	v_mov_b32_e32 v44, v22
	s_waitcnt vmcnt(2)
	v_pk_mul_f32 v[30:31], v[48:49], v[30:31] op_sel:[1,0] op_sel_hi:[0,1]
	v_pk_mul_f32 v[32:33], v[54:55], v[32:33] op_sel:[1,0] op_sel_hi:[0,1]
	v_mov_b32_e32 v45, v24
	v_mov_b32_e32 v24, v23
	v_mov_b32_e32 v22, v26
	v_mov_b32_e32 v23, v28
	v_mov_b32_e32 v28, v27
	ds_bpermute_b32 v26, v67, v18
	ds_bpermute_b32 v27, v67, v19
	ds_bpermute_b32 v48, v67, v20
	ds_bpermute_b32 v49, v67, v21
	ds_bpermute_b32 v54, v67, v30
	ds_bpermute_b32 v55, v67, v31
	ds_bpermute_b32 v56, v67, v32
	ds_bpermute_b32 v57, v67, v33
	s_waitcnt vmcnt(1)
	v_mov_b32_e32 v47, v36
	v_mov_b32_e32 v36, v35
	s_waitcnt vmcnt(0)
	v_mov_b32_e32 v35, v40
	v_mov_b32_e32 v40, v39
	s_waitcnt lgkmcnt(6)
	v_pk_mul_f32 v[24:25], v[24:25], v[26:27]
	s_waitcnt lgkmcnt(4)
	v_pk_mul_f32 v[26:27], v[28:29], v[48:49]
	s_waitcnt lgkmcnt(2)
	v_pk_mul_f32 v[28:29], v[36:37], v[54:55]
	s_waitcnt lgkmcnt(0)
	v_pk_mul_f32 v[36:37], v[40:41], v[56:57]
	v_mov_b32_e32 v46, v34
	v_mov_b32_e32 v34, v38
	v_cndmask_b32_e64 v25, v25, -v25, s[40:41]
	v_cndmask_b32_e64 v24, v24, -v24, s[40:41]
	v_cndmask_b32_e64 v39, v27, -v27, s[40:41]
	v_cndmask_b32_e64 v38, v26, -v26, s[40:41]
	v_cndmask_b32_e64 v29, v29, -v29, s[40:41]
	v_cndmask_b32_e64 v28, v28, -v28, s[40:41]
	v_cndmask_b32_e64 v37, v37, -v37, s[40:41]
	v_cndmask_b32_e64 v36, v36, -v36, s[40:41]
	v_pk_fma_f32 v[26:27], v[18:19], v[44:45], v[24:25]
	v_pk_fma_f32 v[22:23], v[20:21], v[22:23], v[38:39]
	v_pk_fma_f32 v[18:19], v[30:31], v[46:47], v[28:29]
	v_pk_fma_f32 v[20:21], v[32:33], v[34:35], v[36:37]
	v_lshl_add_u64 v[38:39], v[42:43], 0, s[80:81]
.LBB0_161:
	v_cvt_pk_bf16_f32 v24, v26, v27
	v_cvt_pk_bf16_f32 v26, v18, v19
	v_mov_b32_e32 v18, v51
	v_mov_b32_e32 v19, v52
	v_mov_b32_e32 v51, v53
	v_pk_add_f32 v[18:19], v[18:19], v[50:51]
	v_cvt_pk_bf16_f32 v25, v22, v23
	v_add_f32_e32 v18, v18, v19
	v_fmamk_f32 v18, v18, 0x3c000000, v245
	v_mul_f32_e32 v19, 0x4b800000, v18
	v_cmp_gt_f32_e32 vcc, s83, v18
	v_cvt_pk_bf16_f32 v27, v20, v21
	v_subrev_u32_e32 v20, s66, v38
	v_cndmask_b32_e32 v18, v18, v19, vcc
	v_rsq_f32_e32 v18, v18
	s_mov_b32 s58, s62
	s_mov_b32 s59, s63
	buffer_store_dwordx4 v[24:27], v20, s[56:59], 0 offen
	v_mul_f32_e32 v19, 0x45800000, v18
	v_cndmask_b32_e32 v20, v18, v19, vcc
	v_pk_mul_f32 v[14:15], v[14:15], v[20:21] op_sel_hi:[1,0]
	v_pk_mul_f32 v[16:17], v[16:17], v[20:21] op_sel_hi:[1,0]
	v_pk_mul_f32 v[18:19], v[10:11], v[20:21] op_sel_hi:[1,0]
	v_pk_mul_f32 v[12:13], v[12:13], v[20:21] op_sel_hi:[1,0]
	v_and_b32_e32 v21, 0x7ff, v180
	s_and_b64 vcc, exec, s[44:45]
	s_mov_b64 s[2:3], -1
	s_cbranch_vccnz .LBB0_163
	v_lshlrev_b32_e32 v10, 7, v21
	v_mov_b32_e32 v11, v1
	v_lshl_add_u64 v[22:23], v[64:65], 0, v[10:11]
	v_or3_b32 v10, v10, v0, v74
	v_lshl_add_u64 v[26:27], v[22:23], 0, v[0:1]
	v_cvt_pk_bf16_f32 v22, v14, v15
	v_cvt_pk_bf16_f32 v23, v16, v17
	v_cvt_pk_bf16_f32 v24, v18, v19
	v_cvt_pk_bf16_f32 v25, v12, v13
	v_add_u32_e32 v10, 0x17a00000, v10
	buffer_store_dwordx4 v[22:25], v10, s[56:59], 0 offen
	s_mov_b64 s[2:3], 0
	s_nop 0
	v_lshl_add_u64 v[22:23], v[26:27], 0, 64
; #define wt16(p, v) wt16b(WSB, (p), (v))
; __device__ __forceinline__ u32x4 pack8(const float (&f)[8]) { u32x4 v; v.x = cvt_pk_bf16(f[0], f[1]); v.y = cvt_pk_bf16(f[2], f[3]); v.z = cvt_pk_bf16(f[4], f[5]); v.w = cvt_pk_bf16(f[6], f[7]); return v; }
;     __device__ __forceinline__ void operator()(const f32x4 (&acc)[2][2][4][2], const pg8::Unit& u, int wr, int wc, int fr, int fq) const {
;     ...
;                 if (pn < 2) {
;                     const int head = 4 * pn + wc;
;                     float ssn = 0.f;
; #pragma unroll
;                     for (int bj = 0; bj < 2; ++bj)
; #pragma unroll
;                         for (int e = 0; e < 8; ++e) ssn += v[bj][e] * v[bj][e];
;                     float pe[8]; unpack8(*(const u32x4*)(U + (size_t)row * NU + UPE + 8 * fq), pe);
; #pragma unroll
;                     for (int e = 0; e < 8; ++e) ssn += pe[e] * pe[e];
;                     ssn += __shfl_xor(ssn, 16); ssn += __shfl_xor(ssn, 32);
;                     const float rk = rsqrtf(ssn * (1.f / 96.f) + EPS);
;                     bf16_t* kb = Kf + ((size_t)(b * 8 + head) * SEQ + s) * 96;
; #pragma unroll
;                     for (int bj = 0; bj < 2; ++bj) {
;                         float o[8];
; #pragma unroll
;                         for (int e = 0; e < 8; ++e) o[e] = v[bj][e] * rk * khn[32 * bj + 8 * fq + e];
;                         wt16(kb + 32 * bj + 8 * fq, pack8(o));
;                     }
;                     float o[8];
; #pragma unroll
;                     for (int e = 0; e < 8; ++e) {
;                         const float mine = pe[e] * rk * khn[64 + 8 * fq + e];
;                         const float other = __shfl_xor(mine, 32);
;                         const float2 c = cs[(size_t)row * 16 + ((8 * fq + e) & 15)];
;                         o[e] = (fq < 2) ? (mine * c.x - other * c.y) : (other * c.y + mine * c.x);
;                     }
;                     wt16(kb + 64 + 8 * fq, pack8(o));
.LBB0_163:
	v_pk_mul_f32 v[10:11], v[6:7], v[20:21] op_sel_hi:[1,0]
	v_pk_mul_f32 v[6:7], v[8:9], v[20:21] op_sel_hi:[1,0]
	v_pk_mul_f32 v[2:3], v[2:3], v[20:21] op_sel_hi:[1,0]
	s_andn2_b64 vcc, exec, s[2:3]
	v_pk_mul_f32 v[4:5], v[4:5], v[20:21] op_sel_hi:[1,0]
	s_cbranch_vccnz .LBB0_121
	v_mov_b64_e32 v[8:9], s[70:71]
	v_mad_i64_i32 v[8:9], s[2:3], v180, s85, v[8:9]
	v_lshl_add_u64 v[8:9], v[8:9], 0, v[0:1]
	v_add_co_u32_e32 v8, vcc, 0x1000, v8
	v_pk_mul_f32 v[34:35], v[16:17], v[16:17]
	s_nop 0
	v_addc_co_u32_e32 v9, vcc, 0, v9, vcc
	global_load_dwordx4 v[22:25], v[8:9], off offset:1792
	global_load_dwordx4 v[26:29], v[170:171], off
	global_load_dwordx4 v[30:33], v[170:171], off offset:16
	v_pk_mul_f32 v[8:9], v[14:15], v[14:15]
	v_pk_mul_f32 v[36:37], v[18:19], v[18:19]
	v_add_f32_e32 v8, v8, v9
	v_add_f32_e32 v8, v34, v8
	v_add_f32_e32 v8, v35, v8
	v_add_f32_e32 v8, v36, v8
	v_pk_mul_f32 v[38:39], v[12:13], v[12:13]
	v_add_f32_e32 v8, v37, v8
	v_add_f32_e32 v8, v38, v8
	v_pk_mul_f32 v[40:41], v[10:11], v[10:11]
	v_add_f32_e32 v8, v39, v8
	v_add_f32_e32 v8, v40, v8
	v_pk_mul_f32 v[42:43], v[6:7], v[6:7]
	v_add_f32_e32 v8, v41, v8
	v_add_f32_e32 v8, v42, v8
	v_pk_mul_f32 v[44:45], v[2:3], v[2:3]
	v_add_f32_e32 v8, v43, v8
	v_add_f32_e32 v8, v44, v8
	v_pk_mul_f32 v[46:47], v[4:5], v[4:5]
	v_add_f32_e32 v8, v45, v8
	v_add_f32_e32 v8, v46, v8
	v_and_b32_e32 v48, 64, v247
	v_add_f32_e32 v44, v47, v8
	v_xor_b32_e32 v20, 16, v247
	v_add_u32_e32 v48, 64, v48
	v_cmp_lt_i32_e32 vcc, v20, v48
	s_movk_i32 s21, 0xc0
	s_mov_b32 s58, s62
	v_cndmask_b32_e32 v9, v247, v20, vcc
	v_lshlrev_b32_e32 v20, 2, v9
	s_mov_b32 s59, s63
	v_readlane_b32 s2, v253, 32
	v_readlane_b32 s3, v253, 33
	s_waitcnt vmcnt(0)
	v_lshlrev_b32_e32 v40, 16, v22
	v_and_b32_e32 v41, 0xffff0000, v22
	v_pk_mul_f32 v[42:43], v[40:41], v[40:41]
	v_lshlrev_b32_e32 v38, 16, v23
	v_and_b32_e32 v39, 0xffff0000, v23
	v_add_f32_e32 v42, v44, v42
	v_and_b32_e32 v34, 0xffff0000, v24
	v_lshlrev_b32_e32 v35, 16, v24
	v_and_b32_e32 v36, 0xffff0000, v25
	v_lshlrev_b32_e32 v37, 16, v25
	v_pk_mul_f32 v[24:25], v[38:39], v[38:39]
	v_add_f32_e32 v42, v43, v42
	v_add_f32_e32 v24, v24, v42
	v_pk_mul_f32 v[8:9], v[34:35], v[34:35]
	v_add_f32_e32 v24, v25, v24
	v_add_f32_e32 v9, v9, v24
	v_pk_mul_f32 v[22:23], v[36:37], v[36:37]
	v_add_f32_e32 v8, v8, v9
	v_add_f32_e32 v8, v23, v8
	v_add_f32_e32 v8, v22, v8
	ds_bpermute_b32 v9, v20, v8
	v_xor_b32_e32 v20, 32, v247
	v_cmp_lt_i32_e32 vcc, v20, v48
	v_or_b32_e32 v44, v62, v21
	s_waitcnt lgkmcnt(0)
	v_add_f32_e32 v8, v8, v9
	v_cndmask_b32_e32 v20, v247, v20, vcc
	v_lshlrev_b32_e32 v43, 2, v20
	ds_bpermute_b32 v9, v43, v8
	v_mul_lo_u32 v20, v44, s21
	v_add_u32_e32 v21, v20, v172
	v_add_u32_e32 v20, v174, v20
	s_waitcnt lgkmcnt(0)
	v_add_f32_e32 v8, v8, v9
	v_fmamk_f32 v8, v8, 0x3c2aaaab, v245
	v_mul_f32_e32 v9, 0x4b800000, v8
	v_cmp_gt_f32_e32 vcc, s83, v8
	s_nop 1
	v_cndmask_b32_e32 v8, v8, v9, vcc
	v_rsq_f32_e32 v8, v8
	s_nop 0
	v_mul_f32_e32 v9, 0x45800000, v8
	v_cndmask_b32_e32 v42, v8, v9, vcc
	v_pk_mul_f32 v[8:9], v[14:15], v[42:43] op_sel_hi:[1,0]
	v_pk_mul_f32 v[14:15], v[16:17], v[42:43] op_sel_hi:[1,0]
	v_pk_mul_f32 v[16:17], v[18:19], v[42:43] op_sel_hi:[1,0]
	v_pk_mul_f32 v[12:13], v[12:13], v[42:43] op_sel_hi:[1,0]
	v_pk_mul_f32 v[8:9], v[26:27], v[8:9]
	v_pk_mul_f32 v[14:15], v[28:29], v[14:15]
	v_pk_mul_f32 v[16:17], v[30:31], v[16:17]
	v_pk_mul_f32 v[18:19], v[32:33], v[12:13]
	v_cvt_pk_bf16_f32 v12, v8, v9
	v_cvt_pk_bf16_f32 v13, v14, v15
	v_cvt_pk_bf16_f32 v14, v16, v17
	v_cvt_pk_bf16_f32 v15, v18, v19
	buffer_store_dwordx4 v[12:15], v21, s[56:59], 0 offen
	global_load_dwordx4 v[12:15], v[170:171], off offset:128
	s_nop 0
	global_load_dwordx4 v[16:19], v[170:171], off offset:144
	v_lshlrev_b64 v[8:9], 7, v[180:181]
	v_lshl_add_u64 v[22:23], v[168:169], 0, v[8:9]
	v_pk_mul_f32 v[8:9], v[10:11], v[42:43] op_sel_hi:[1,0]
	v_pk_mul_f32 v[6:7], v[6:7], v[42:43] op_sel_hi:[1,0]
	v_pk_mul_f32 v[2:3], v[2:3], v[42:43] op_sel_hi:[1,0]
	v_pk_mul_f32 v[4:5], v[4:5], v[42:43] op_sel_hi:[1,0]
	v_pk_mul_f32 v[28:29], v[42:43], v[40:41] op_sel_hi:[0,1]
	v_pk_mul_f32 v[30:31], v[42:43], v[38:39] op_sel_hi:[0,1]
	v_pk_mul_f32 v[32:33], v[42:43], v[34:35] op_sel_hi:[0,1]
	v_pk_mul_f32 v[34:35], v[42:43], v[36:37] op_sel_hi:[0,1]
	v_mov_b64_e32 v[26:27], s[2:3]
	v_mad_u64_u32 v[26:27], s[2:3], v44, s21, v[26:27]
	v_mad_i32_i24 v27, v63, s21, v27
	v_lshl_add_u64 v[26:27], v[26:27], 0, v[0:1]
	s_waitcnt vmcnt(1)
	v_pk_mul_f32 v[8:9], v[12:13], v[8:9]
	v_pk_mul_f32 v[6:7], v[14:15], v[6:7]
	s_waitcnt vmcnt(0)
	v_pk_mul_f32 v[10:11], v[16:17], v[2:3]
	v_pk_mul_f32 v[12:13], v[18:19], v[4:5]
	v_cvt_pk_bf16_f32 v2, v8, v9
	v_cvt_pk_bf16_f32 v3, v6, v7
	v_cvt_pk_bf16_f32 v4, v10, v11
	v_cvt_pk_bf16_f32 v5, v12, v13
	buffer_store_dwordx4 v[2:5], v20, s[56:59], 0 offen
	global_load_dwordx4 v[2:5], v[170:171], off offset:256
	s_nop 0
	global_load_dwordx4 v[6:9], v[22:23], off
	global_load_dwordx4 v[10:13], v[22:23], off offset:16
	global_load_dwordx4 v[14:17], v[170:171], off offset:272
	global_load_dwordx4 v[18:21], v[22:23], off offset:32
	s_nop 0
	global_load_dwordx4 v[22:25], v[22:23], off offset:48
	s_waitcnt vmcnt(5)
	v_pk_mul_f32 v[2:3], v[28:29], v[2:3]
	v_pk_mul_f32 v[4:5], v[30:31], v[4:5]
	s_waitcnt vmcnt(4)
	v_mov_b32_e32 v28, v6
	s_waitcnt vmcnt(2)
	v_pk_mul_f32 v[14:15], v[32:33], v[14:15] op_sel:[1,0] op_sel_hi:[0,1]
	v_pk_mul_f32 v[16:17], v[34:35], v[16:17] op_sel:[1,0] op_sel_hi:[0,1]
	v_mov_b32_e32 v29, v8
	v_mov_b32_e32 v8, v7
	v_mov_b32_e32 v6, v10
	v_mov_b32_e32 v7, v12
	v_mov_b32_e32 v12, v11
	ds_bpermute_b32 v10, v43, v2
	ds_bpermute_b32 v11, v43, v3
	ds_bpermute_b32 v32, v43, v4
	ds_bpermute_b32 v33, v43, v5
	ds_bpermute_b32 v34, v43, v14
	ds_bpermute_b32 v35, v43, v15
	ds_bpermute_b32 v36, v43, v16
	ds_bpermute_b32 v37, v43, v17
	s_waitcnt vmcnt(1)
	v_mov_b32_e32 v31, v20
	v_mov_b32_e32 v20, v19
	s_waitcnt vmcnt(0)
	v_mov_b32_e32 v19, v24
	v_mov_b32_e32 v24, v23
	s_waitcnt lgkmcnt(6)
	v_pk_mul_f32 v[8:9], v[8:9], v[10:11]
	s_waitcnt lgkmcnt(4)
	v_pk_mul_f32 v[10:11], v[12:13], v[32:33]
	s_waitcnt lgkmcnt(2)
	v_pk_mul_f32 v[12:13], v[20:21], v[34:35]
	s_waitcnt lgkmcnt(0)
	v_pk_mul_f32 v[20:21], v[24:25], v[36:37]
	v_mov_b32_e32 v30, v18
	v_mov_b32_e32 v18, v22
	v_cndmask_b32_e64 v9, v9, -v9, s[40:41]
	v_cndmask_b32_e64 v8, v8, -v8, s[40:41]
	v_cndmask_b32_e64 v23, v11, -v11, s[40:41]
	v_cndmask_b32_e64 v22, v10, -v10, s[40:41]
	v_cndmask_b32_e64 v13, v13, -v13, s[40:41]
	v_cndmask_b32_e64 v12, v12, -v12, s[40:41]
	v_cndmask_b32_e64 v21, v21, -v21, s[40:41]
	v_cndmask_b32_e64 v20, v20, -v20, s[40:41]
	v_pk_fma_f32 v[10:11], v[2:3], v[28:29], v[8:9]
	v_pk_fma_f32 v[6:7], v[4:5], v[6:7], v[22:23]
	v_pk_fma_f32 v[2:3], v[14:15], v[30:31], v[12:13]
	v_pk_fma_f32 v[4:5], v[16:17], v[18:19], v[20:21]
	v_lshl_add_u64 v[22:23], v[26:27], 0, s[80:81]
	s_branch .LBB0_121
